# xattn: V batch-1 global loads hoisted ahead of the softmax (land during VALU work); on top of pipelined QK stream
# speedup vs baseline: 1.0160x; 1.0046x over previous
.LBB0_760:
	v_add_u32_e32 v181, 0x11800, v211
	v_add_u32_e32 v220, 0x15e00, v211
	v_add_u32_e32 v221, 0x1a400, v211
	v_add_u32_e32 v222, 0x1ea00, v211
	global_load_dwordx4 v[212:215], v[170:171], off offset:-128
	global_load_dwordx4 v[216:219], v[170:171], off offset:-96
	global_load_dwordx4 v[248:251], v[170:171], off offset:-64
	ds_read_b128 v[224:227], v211
	ds_read_b128 v[228:231], v211 offset:17920
	ds_read_b128 v[232:235], v211 offset:35840
	ds_read_b128 v[236:239], v211 offset:53760
	ds_read_b128 v[240:243], v181
	ds_read_b128 v[244:247], v220
	s_waitcnt vmcnt(2) lgkmcnt(5)
	v_mfma_f32_32x32x16_bf16 v[112:127], v[224:227], v[212:215], 0
	ds_read_b128 v[224:227], v221
	s_waitcnt lgkmcnt(5)
	v_mfma_f32_32x32x16_bf16 v[96:111], v[228:231], v[212:215], 0
	ds_read_b128 v[228:231], v222
	s_waitcnt lgkmcnt(5)
	v_mfma_f32_32x32x16_bf16 v[80:95], v[232:235], v[212:215], 0
	ds_read_b128 v[232:235], v211 offset:32
	s_waitcnt lgkmcnt(5)
	v_mfma_f32_32x32x16_bf16 v[64:79], v[236:239], v[212:215], 0
	ds_read_b128 v[236:239], v211 offset:17952
	s_waitcnt lgkmcnt(5)
	v_mfma_f32_32x32x16_bf16 v[48:63], v[240:243], v[212:215], 0
	ds_read_b128 v[240:243], v211 offset:35872
	s_waitcnt lgkmcnt(5)
	v_mfma_f32_32x32x16_bf16 v[32:47], v[244:247], v[212:215], 0
	ds_read_b128 v[244:247], v211 offset:53792
	s_waitcnt lgkmcnt(5)
	v_mfma_f32_32x32x16_bf16 v[16:31], v[224:227], v[212:215], 0
	ds_read_b128 v[224:227], v181 offset:32
	s_waitcnt lgkmcnt(5)
	v_mfma_f32_32x32x16_bf16 v[0:15], v[228:231], v[212:215], 0
	ds_read_b128 v[228:231], v220 offset:32
	global_load_dwordx4 v[212:215], v[170:171], off offset:-32
	s_waitcnt vmcnt(2) lgkmcnt(5)
	v_mfma_f32_32x32x16_bf16 v[112:127], v[232:235], v[216:219], v[112:127]
	ds_read_b128 v[232:235], v221 offset:32
	s_waitcnt lgkmcnt(5)
	v_mfma_f32_32x32x16_bf16 v[96:111], v[236:239], v[216:219], v[96:111]
	ds_read_b128 v[236:239], v222 offset:32
	s_waitcnt lgkmcnt(5)
	v_mfma_f32_32x32x16_bf16 v[80:95], v[240:243], v[216:219], v[80:95]
	ds_read_b128 v[240:243], v211 offset:64
	s_waitcnt lgkmcnt(5)
	v_mfma_f32_32x32x16_bf16 v[64:79], v[244:247], v[216:219], v[64:79]
	ds_read_b128 v[244:247], v211 offset:17984
	s_waitcnt lgkmcnt(5)
	v_mfma_f32_32x32x16_bf16 v[48:63], v[224:227], v[216:219], v[48:63]
	ds_read_b128 v[224:227], v211 offset:35904
	s_waitcnt lgkmcnt(5)
	v_mfma_f32_32x32x16_bf16 v[32:47], v[228:231], v[216:219], v[32:47]
	ds_read_b128 v[228:231], v211 offset:53824
	s_waitcnt lgkmcnt(5)
	v_mfma_f32_32x32x16_bf16 v[16:31], v[232:235], v[216:219], v[16:31]
	ds_read_b128 v[232:235], v181 offset:64
	s_waitcnt lgkmcnt(5)
	v_mfma_f32_32x32x16_bf16 v[0:15], v[236:239], v[216:219], v[0:15]
	ds_read_b128 v[236:239], v220 offset:64
	global_load_dwordx4 v[216:219], v[170:171], off
	s_waitcnt vmcnt(2) lgkmcnt(5)
	v_mfma_f32_32x32x16_bf16 v[112:127], v[240:243], v[248:251], v[112:127]
	ds_read_b128 v[240:243], v221 offset:64
	s_waitcnt lgkmcnt(5)
	v_mfma_f32_32x32x16_bf16 v[96:111], v[244:247], v[248:251], v[96:111]
	ds_read_b128 v[244:247], v222 offset:64
	s_waitcnt lgkmcnt(5)
	v_mfma_f32_32x32x16_bf16 v[80:95], v[224:227], v[248:251], v[80:95]
	ds_read_b128 v[224:227], v211 offset:96
	s_waitcnt lgkmcnt(5)
	v_mfma_f32_32x32x16_bf16 v[64:79], v[228:231], v[248:251], v[64:79]
	ds_read_b128 v[228:231], v211 offset:18016
	s_waitcnt lgkmcnt(5)
	v_mfma_f32_32x32x16_bf16 v[48:63], v[232:235], v[248:251], v[48:63]
	ds_read_b128 v[232:235], v211 offset:35936
	s_waitcnt lgkmcnt(5)
	v_mfma_f32_32x32x16_bf16 v[32:47], v[236:239], v[248:251], v[32:47]
	ds_read_b128 v[236:239], v211 offset:53856
	s_waitcnt lgkmcnt(5)
	v_mfma_f32_32x32x16_bf16 v[16:31], v[240:243], v[248:251], v[16:31]
	ds_read_b128 v[240:243], v181 offset:96
	s_waitcnt lgkmcnt(5)
	v_mfma_f32_32x32x16_bf16 v[0:15], v[244:247], v[248:251], v[0:15]
	ds_read_b128 v[244:247], v220 offset:96
	global_load_dwordx4 v[248:251], v[170:171], off offset:32
	s_waitcnt vmcnt(2) lgkmcnt(5)
	v_mfma_f32_32x32x16_bf16 v[112:127], v[224:227], v[212:215], v[112:127]
	ds_read_b128 v[224:227], v221 offset:96
	s_waitcnt lgkmcnt(5)
	v_mfma_f32_32x32x16_bf16 v[96:111], v[228:231], v[212:215], v[96:111]
	ds_read_b128 v[228:231], v222 offset:96
	s_waitcnt lgkmcnt(5)
	v_mfma_f32_32x32x16_bf16 v[80:95], v[232:235], v[212:215], v[80:95]
	ds_read_b128 v[232:235], v211 offset:128
	s_waitcnt lgkmcnt(5)
	v_mfma_f32_32x32x16_bf16 v[64:79], v[236:239], v[212:215], v[64:79]
	ds_read_b128 v[236:239], v211 offset:18048
	s_waitcnt lgkmcnt(5)
	v_mfma_f32_32x32x16_bf16 v[48:63], v[240:243], v[212:215], v[48:63]
	ds_read_b128 v[240:243], v211 offset:35968
	s_waitcnt lgkmcnt(5)
	v_mfma_f32_32x32x16_bf16 v[32:47], v[244:247], v[212:215], v[32:47]
	ds_read_b128 v[244:247], v211 offset:53888
	s_waitcnt lgkmcnt(5)
	v_mfma_f32_32x32x16_bf16 v[16:31], v[224:227], v[212:215], v[16:31]
	ds_read_b128 v[224:227], v181 offset:128
	s_waitcnt lgkmcnt(5)
	v_mfma_f32_32x32x16_bf16 v[0:15], v[228:231], v[212:215], v[0:15]
	ds_read_b128 v[228:231], v220 offset:128
	global_load_dwordx4 v[212:215], v[170:171], off offset:64
	s_waitcnt vmcnt(2) lgkmcnt(5)
	v_mfma_f32_32x32x16_bf16 v[112:127], v[232:235], v[216:219], v[112:127]
	ds_read_b128 v[232:235], v221 offset:128
	s_waitcnt lgkmcnt(5)
	v_mfma_f32_32x32x16_bf16 v[96:111], v[236:239], v[216:219], v[96:111]
	ds_read_b128 v[236:239], v222 offset:128
	s_waitcnt lgkmcnt(5)
	v_mfma_f32_32x32x16_bf16 v[80:95], v[240:243], v[216:219], v[80:95]
	ds_read_b128 v[240:243], v211 offset:160
	s_waitcnt lgkmcnt(5)
	v_mfma_f32_32x32x16_bf16 v[64:79], v[244:247], v[216:219], v[64:79]
	ds_read_b128 v[244:247], v211 offset:18080
	s_waitcnt lgkmcnt(5)
	v_mfma_f32_32x32x16_bf16 v[48:63], v[224:227], v[216:219], v[48:63]
	ds_read_b128 v[224:227], v211 offset:36000
	s_waitcnt lgkmcnt(5)
	v_mfma_f32_32x32x16_bf16 v[32:47], v[228:231], v[216:219], v[32:47]
	ds_read_b128 v[228:231], v211 offset:53920
	s_waitcnt lgkmcnt(5)
	v_mfma_f32_32x32x16_bf16 v[16:31], v[232:235], v[216:219], v[16:31]
	ds_read_b128 v[232:235], v181 offset:160
	s_waitcnt lgkmcnt(5)
	v_mfma_f32_32x32x16_bf16 v[0:15], v[236:239], v[216:219], v[0:15]
	ds_read_b128 v[236:239], v220 offset:160
	global_load_dwordx4 v[216:219], v[170:171], off offset:96
	s_waitcnt vmcnt(2) lgkmcnt(5)
	v_mfma_f32_32x32x16_bf16 v[112:127], v[240:243], v[248:251], v[112:127]
	ds_read_b128 v[240:243], v221 offset:160
	s_waitcnt lgkmcnt(5)
	v_mfma_f32_32x32x16_bf16 v[96:111], v[244:247], v[248:251], v[96:111]
	ds_read_b128 v[244:247], v222 offset:160
	s_waitcnt lgkmcnt(5)
	v_mfma_f32_32x32x16_bf16 v[80:95], v[224:227], v[248:251], v[80:95]
	ds_read_b128 v[224:227], v211 offset:192
	s_waitcnt lgkmcnt(5)
	v_mfma_f32_32x32x16_bf16 v[64:79], v[228:231], v[248:251], v[64:79]
	ds_read_b128 v[228:231], v211 offset:18112
	s_waitcnt lgkmcnt(5)
	v_mfma_f32_32x32x16_bf16 v[48:63], v[232:235], v[248:251], v[48:63]
	ds_read_b128 v[232:235], v211 offset:36032
	s_waitcnt lgkmcnt(5)
	v_mfma_f32_32x32x16_bf16 v[32:47], v[236:239], v[248:251], v[32:47]
	ds_read_b128 v[236:239], v211 offset:53952
	s_waitcnt lgkmcnt(5)
	v_mfma_f32_32x32x16_bf16 v[16:31], v[240:243], v[248:251], v[16:31]
	ds_read_b128 v[240:243], v181 offset:192
	s_waitcnt lgkmcnt(5)
	v_mfma_f32_32x32x16_bf16 v[0:15], v[244:247], v[248:251], v[0:15]
	ds_read_b128 v[244:247], v220 offset:192
	global_load_dwordx4 v[248:251], v[170:171], off offset:128
	s_waitcnt vmcnt(2) lgkmcnt(5)
	v_mfma_f32_32x32x16_bf16 v[112:127], v[224:227], v[212:215], v[112:127]
	ds_read_b128 v[224:227], v221 offset:192
	s_waitcnt lgkmcnt(5)
	v_mfma_f32_32x32x16_bf16 v[96:111], v[228:231], v[212:215], v[96:111]
	ds_read_b128 v[228:231], v222 offset:192
	s_waitcnt lgkmcnt(5)
	v_mfma_f32_32x32x16_bf16 v[80:95], v[232:235], v[212:215], v[80:95]
	ds_read_b128 v[232:235], v211 offset:224
	s_waitcnt lgkmcnt(5)
	v_mfma_f32_32x32x16_bf16 v[64:79], v[236:239], v[212:215], v[64:79]
	ds_read_b128 v[236:239], v211 offset:18144
	s_waitcnt lgkmcnt(5)
	v_mfma_f32_32x32x16_bf16 v[48:63], v[240:243], v[212:215], v[48:63]
	ds_read_b128 v[240:243], v211 offset:36064
	s_waitcnt lgkmcnt(5)
	v_mfma_f32_32x32x16_bf16 v[32:47], v[244:247], v[212:215], v[32:47]
	ds_read_b128 v[244:247], v211 offset:53984
	s_waitcnt lgkmcnt(5)
	v_mfma_f32_32x32x16_bf16 v[16:31], v[224:227], v[212:215], v[16:31]
	ds_read_b128 v[224:227], v181 offset:224
	s_waitcnt lgkmcnt(5)
	v_mfma_f32_32x32x16_bf16 v[0:15], v[228:231], v[212:215], v[0:15]
	ds_read_b128 v[228:231], v220 offset:224
	global_load_dwordx4 v[212:215], v[170:171], off offset:160
	s_waitcnt vmcnt(2) lgkmcnt(5)
	v_mfma_f32_32x32x16_bf16 v[112:127], v[232:235], v[216:219], v[112:127]
	ds_read_b128 v[232:235], v221 offset:224
	s_waitcnt lgkmcnt(5)
	v_mfma_f32_32x32x16_bf16 v[96:111], v[236:239], v[216:219], v[96:111]
	ds_read_b128 v[236:239], v222 offset:224
	s_waitcnt lgkmcnt(5)
	v_mfma_f32_32x32x16_bf16 v[80:95], v[240:243], v[216:219], v[80:95]
	ds_read_b128 v[240:243], v211 offset:256
	s_waitcnt lgkmcnt(5)
	v_mfma_f32_32x32x16_bf16 v[64:79], v[244:247], v[216:219], v[64:79]
	ds_read_b128 v[244:247], v211 offset:18176
	s_waitcnt lgkmcnt(5)
	v_mfma_f32_32x32x16_bf16 v[48:63], v[224:227], v[216:219], v[48:63]
	ds_read_b128 v[224:227], v211 offset:36096
	s_waitcnt lgkmcnt(5)
	v_mfma_f32_32x32x16_bf16 v[32:47], v[228:231], v[216:219], v[32:47]
	ds_read_b128 v[228:231], v211 offset:54016
	s_waitcnt lgkmcnt(5)
	v_mfma_f32_32x32x16_bf16 v[16:31], v[232:235], v[216:219], v[16:31]
	ds_read_b128 v[232:235], v181 offset:256
	s_waitcnt lgkmcnt(5)
	v_mfma_f32_32x32x16_bf16 v[0:15], v[236:239], v[216:219], v[0:15]
	ds_read_b128 v[236:239], v220 offset:256
	global_load_dwordx4 v[216:219], v[170:171], off offset:192
	s_waitcnt vmcnt(2) lgkmcnt(5)
	v_mfma_f32_32x32x16_bf16 v[112:127], v[240:243], v[248:251], v[112:127]
	ds_read_b128 v[240:243], v221 offset:256
	s_waitcnt lgkmcnt(5)
	v_mfma_f32_32x32x16_bf16 v[96:111], v[244:247], v[248:251], v[96:111]
	ds_read_b128 v[244:247], v222 offset:256
	s_waitcnt lgkmcnt(5)
	v_mfma_f32_32x32x16_bf16 v[80:95], v[224:227], v[248:251], v[80:95]
	ds_read_b128 v[224:227], v211 offset:288
	s_waitcnt lgkmcnt(5)
	v_mfma_f32_32x32x16_bf16 v[64:79], v[228:231], v[248:251], v[64:79]
	ds_read_b128 v[228:231], v211 offset:18208
	s_waitcnt lgkmcnt(5)
	v_mfma_f32_32x32x16_bf16 v[48:63], v[232:235], v[248:251], v[48:63]
	ds_read_b128 v[232:235], v211 offset:36128
	s_waitcnt lgkmcnt(5)
	v_mfma_f32_32x32x16_bf16 v[32:47], v[236:239], v[248:251], v[32:47]
	ds_read_b128 v[236:239], v211 offset:54048
	s_waitcnt lgkmcnt(5)
	v_mfma_f32_32x32x16_bf16 v[16:31], v[240:243], v[248:251], v[16:31]
	ds_read_b128 v[240:243], v181 offset:288
	s_waitcnt lgkmcnt(5)
	v_mfma_f32_32x32x16_bf16 v[0:15], v[244:247], v[248:251], v[0:15]
	ds_read_b128 v[244:247], v220 offset:288
	global_load_dwordx4 v[248:251], v[170:171], off offset:224
	s_waitcnt vmcnt(2) lgkmcnt(5)
	v_mfma_f32_32x32x16_bf16 v[112:127], v[224:227], v[212:215], v[112:127]
	ds_read_b128 v[224:227], v221 offset:288
	s_waitcnt lgkmcnt(5)
	v_mfma_f32_32x32x16_bf16 v[96:111], v[228:231], v[212:215], v[96:111]
	ds_read_b128 v[228:231], v222 offset:288
	s_waitcnt lgkmcnt(5)
	v_mfma_f32_32x32x16_bf16 v[80:95], v[232:235], v[212:215], v[80:95]
	ds_read_b128 v[232:235], v211 offset:320
	s_waitcnt lgkmcnt(5)
	v_mfma_f32_32x32x16_bf16 v[64:79], v[236:239], v[212:215], v[64:79]
	ds_read_b128 v[236:239], v211 offset:18240
	s_waitcnt lgkmcnt(5)
	v_mfma_f32_32x32x16_bf16 v[48:63], v[240:243], v[212:215], v[48:63]
	ds_read_b128 v[240:243], v211 offset:36160
	s_waitcnt lgkmcnt(5)
	v_mfma_f32_32x32x16_bf16 v[32:47], v[244:247], v[212:215], v[32:47]
	ds_read_b128 v[244:247], v211 offset:54080
	s_waitcnt lgkmcnt(5)
	v_mfma_f32_32x32x16_bf16 v[16:31], v[224:227], v[212:215], v[16:31]
	ds_read_b128 v[224:227], v181 offset:320
	s_waitcnt lgkmcnt(5)
	v_mfma_f32_32x32x16_bf16 v[0:15], v[228:231], v[212:215], v[0:15]
	ds_read_b128 v[228:231], v220 offset:320
	global_load_dwordx4 v[212:215], v[170:171], off offset:256
	s_waitcnt vmcnt(2) lgkmcnt(5)
	v_mfma_f32_32x32x16_bf16 v[112:127], v[232:235], v[216:219], v[112:127]
	ds_read_b128 v[232:235], v221 offset:320
	s_waitcnt lgkmcnt(5)
	v_mfma_f32_32x32x16_bf16 v[96:111], v[236:239], v[216:219], v[96:111]
	ds_read_b128 v[236:239], v222 offset:320
	s_waitcnt lgkmcnt(5)
	v_mfma_f32_32x32x16_bf16 v[80:95], v[240:243], v[216:219], v[80:95]
	ds_read_b128 v[240:243], v211 offset:352
	s_waitcnt lgkmcnt(5)
	v_mfma_f32_32x32x16_bf16 v[64:79], v[244:247], v[216:219], v[64:79]
	ds_read_b128 v[244:247], v211 offset:18272
	s_waitcnt lgkmcnt(5)
	v_mfma_f32_32x32x16_bf16 v[48:63], v[224:227], v[216:219], v[48:63]
	ds_read_b128 v[224:227], v211 offset:36192
	s_waitcnt lgkmcnt(5)
	v_mfma_f32_32x32x16_bf16 v[32:47], v[228:231], v[216:219], v[32:47]
	ds_read_b128 v[228:231], v211 offset:54112
	s_waitcnt lgkmcnt(5)
	v_mfma_f32_32x32x16_bf16 v[16:31], v[232:235], v[216:219], v[16:31]
	ds_read_b128 v[232:235], v181 offset:352
	s_waitcnt lgkmcnt(5)
	v_mfma_f32_32x32x16_bf16 v[0:15], v[236:239], v[216:219], v[0:15]
	ds_read_b128 v[236:239], v220 offset:352
	global_load_dwordx4 v[216:219], v[170:171], off offset:288
	s_waitcnt vmcnt(2) lgkmcnt(5)
	v_mfma_f32_32x32x16_bf16 v[112:127], v[240:243], v[248:251], v[112:127]
	ds_read_b128 v[240:243], v221 offset:352
	s_waitcnt lgkmcnt(5)
	v_mfma_f32_32x32x16_bf16 v[96:111], v[244:247], v[248:251], v[96:111]
	ds_read_b128 v[244:247], v222 offset:352
	s_waitcnt lgkmcnt(5)
	v_mfma_f32_32x32x16_bf16 v[80:95], v[224:227], v[248:251], v[80:95]
	ds_read_b128 v[224:227], v211 offset:384
	s_waitcnt lgkmcnt(5)
	v_mfma_f32_32x32x16_bf16 v[64:79], v[228:231], v[248:251], v[64:79]
	ds_read_b128 v[228:231], v211 offset:18304
	s_waitcnt lgkmcnt(5)
	v_mfma_f32_32x32x16_bf16 v[48:63], v[232:235], v[248:251], v[48:63]
	ds_read_b128 v[232:235], v211 offset:36224
	s_waitcnt lgkmcnt(5)
	v_mfma_f32_32x32x16_bf16 v[32:47], v[236:239], v[248:251], v[32:47]
	ds_read_b128 v[236:239], v211 offset:54144
	s_waitcnt lgkmcnt(5)
	v_mfma_f32_32x32x16_bf16 v[16:31], v[240:243], v[248:251], v[16:31]
	ds_read_b128 v[240:243], v181 offset:384
	s_waitcnt lgkmcnt(5)
	v_mfma_f32_32x32x16_bf16 v[0:15], v[244:247], v[248:251], v[0:15]
	ds_read_b128 v[244:247], v220 offset:384
	global_load_dwordx4 v[248:251], v[170:171], off offset:320
	s_waitcnt vmcnt(2) lgkmcnt(5)
	v_mfma_f32_32x32x16_bf16 v[112:127], v[224:227], v[212:215], v[112:127]
	ds_read_b128 v[224:227], v221 offset:384
	s_waitcnt lgkmcnt(5)
	v_mfma_f32_32x32x16_bf16 v[96:111], v[228:231], v[212:215], v[96:111]
	ds_read_b128 v[228:231], v222 offset:384
	s_waitcnt lgkmcnt(5)
	v_mfma_f32_32x32x16_bf16 v[80:95], v[232:235], v[212:215], v[80:95]
	ds_read_b128 v[232:235], v211 offset:416
	s_waitcnt lgkmcnt(5)
	v_mfma_f32_32x32x16_bf16 v[64:79], v[236:239], v[212:215], v[64:79]
	ds_read_b128 v[236:239], v211 offset:18336
	s_waitcnt lgkmcnt(5)
	v_mfma_f32_32x32x16_bf16 v[48:63], v[240:243], v[212:215], v[48:63]
	ds_read_b128 v[240:243], v211 offset:36256
	s_waitcnt lgkmcnt(5)
	v_mfma_f32_32x32x16_bf16 v[32:47], v[244:247], v[212:215], v[32:47]
	ds_read_b128 v[244:247], v211 offset:54176
	s_waitcnt lgkmcnt(5)
	v_mfma_f32_32x32x16_bf16 v[16:31], v[224:227], v[212:215], v[16:31]
	ds_read_b128 v[224:227], v181 offset:416
	s_waitcnt lgkmcnt(5)
	v_mfma_f32_32x32x16_bf16 v[0:15], v[228:231], v[212:215], v[0:15]
	ds_read_b128 v[228:231], v220 offset:416
	global_load_dwordx4 v[212:215], v[170:171], off offset:352
	s_waitcnt vmcnt(2) lgkmcnt(5)
	v_mfma_f32_32x32x16_bf16 v[112:127], v[232:235], v[216:219], v[112:127]
	ds_read_b128 v[232:235], v221 offset:416
	s_waitcnt lgkmcnt(5)
	v_mfma_f32_32x32x16_bf16 v[96:111], v[236:239], v[216:219], v[96:111]
	ds_read_b128 v[236:239], v222 offset:416
	s_waitcnt lgkmcnt(5)
	v_mfma_f32_32x32x16_bf16 v[80:95], v[240:243], v[216:219], v[80:95]
	ds_read_b128 v[240:243], v211 offset:448
	s_waitcnt lgkmcnt(5)
	v_mfma_f32_32x32x16_bf16 v[64:79], v[244:247], v[216:219], v[64:79]
	ds_read_b128 v[244:247], v211 offset:18368
	s_waitcnt lgkmcnt(5)
	v_mfma_f32_32x32x16_bf16 v[48:63], v[224:227], v[216:219], v[48:63]
	ds_read_b128 v[224:227], v211 offset:36288
	s_waitcnt lgkmcnt(5)
	v_mfma_f32_32x32x16_bf16 v[32:47], v[228:231], v[216:219], v[32:47]
	ds_read_b128 v[228:231], v211 offset:54208
	s_waitcnt lgkmcnt(5)
	v_mfma_f32_32x32x16_bf16 v[16:31], v[232:235], v[216:219], v[16:31]
	ds_read_b128 v[232:235], v181 offset:448
	s_waitcnt lgkmcnt(5)
	v_mfma_f32_32x32x16_bf16 v[0:15], v[236:239], v[216:219], v[0:15]
	ds_read_b128 v[236:239], v220 offset:448
	s_waitcnt vmcnt(1) lgkmcnt(5)
	v_mfma_f32_32x32x16_bf16 v[112:127], v[240:243], v[248:251], v[112:127]
	ds_read_b128 v[240:243], v221 offset:448
	s_waitcnt lgkmcnt(5)
	v_mfma_f32_32x32x16_bf16 v[96:111], v[244:247], v[248:251], v[96:111]
	ds_read_b128 v[244:247], v222 offset:448
	s_waitcnt lgkmcnt(5)
	v_mfma_f32_32x32x16_bf16 v[80:95], v[224:227], v[248:251], v[80:95]
	ds_read_b128 v[224:227], v211 offset:480
	s_waitcnt lgkmcnt(5)
	v_mfma_f32_32x32x16_bf16 v[64:79], v[228:231], v[248:251], v[64:79]
	ds_read_b128 v[228:231], v211 offset:18400
	s_waitcnt lgkmcnt(5)
	v_mfma_f32_32x32x16_bf16 v[48:63], v[232:235], v[248:251], v[48:63]
	ds_read_b128 v[232:235], v211 offset:36320
	s_waitcnt lgkmcnt(5)
	v_mfma_f32_32x32x16_bf16 v[32:47], v[236:239], v[248:251], v[32:47]
	ds_read_b128 v[236:239], v211 offset:54240
	s_waitcnt lgkmcnt(5)
	v_mfma_f32_32x32x16_bf16 v[16:31], v[240:243], v[248:251], v[16:31]
	ds_read_b128 v[240:243], v181 offset:480
	s_waitcnt lgkmcnt(5)
	v_mfma_f32_32x32x16_bf16 v[0:15], v[244:247], v[248:251], v[0:15]
	ds_read_b128 v[244:247], v220 offset:480
	s_waitcnt vmcnt(0) lgkmcnt(5)
	v_mfma_f32_32x32x16_bf16 v[112:127], v[224:227], v[212:215], v[112:127]
	ds_read_b128 v[224:227], v221 offset:480
	s_waitcnt lgkmcnt(5)
	v_mfma_f32_32x32x16_bf16 v[96:111], v[228:231], v[212:215], v[96:111]
	ds_read_b128 v[228:231], v222 offset:480
	s_waitcnt lgkmcnt(5)
	v_mfma_f32_32x32x16_bf16 v[80:95], v[232:235], v[212:215], v[80:95]
	s_waitcnt lgkmcnt(4)
	v_mfma_f32_32x32x16_bf16 v[64:79], v[236:239], v[212:215], v[64:79]
	s_waitcnt lgkmcnt(3)
	v_mfma_f32_32x32x16_bf16 v[48:63], v[240:243], v[212:215], v[48:63]
	s_waitcnt lgkmcnt(2)
	v_mfma_f32_32x32x16_bf16 v[32:47], v[244:247], v[212:215], v[32:47]
	s_waitcnt lgkmcnt(1)
	v_mfma_f32_32x32x16_bf16 v[16:31], v[224:227], v[212:215], v[16:31]
	s_waitcnt lgkmcnt(0)
	v_mfma_f32_32x32x16_bf16 v[0:15], v[228:231], v[212:215], v[0:15]
	s_movk_i32 s47, 0x200
	v_lshl_add_u64 v[244:245], v[160:161], 0, s[38:39]
	global_load_dwordx4 v[212:215], v[160:161], off offset:2096
	global_load_dwordx4 v[216:219], v[160:161], off offset:2080
	global_load_dwordx4 v[224:227], v[160:161], off offset:2064
	global_load_dwordx4 v[228:231], v[160:161], off offset:2048
	global_load_dwordx4 v[232:235], v[168:169], off offset:2048
	global_load_dwordx4 v[236:239], v[244:245], off offset:48
	global_load_dwordx4 v[240:243], v[244:245], off offset:32
	global_load_dwordx4 v[246:249], v[244:245], off offset:16
	v_mov_b32_e32 v170, v145
	v_mov_b32_e32 v171, v146
	v_mov_b32_e32 v145, v147
	v_mov_b32_e32 v146, v141
	v_mov_b32_e32 v147, v142
	v_mov_b32_e32 v141, v143
	v_pk_add_f32 v[144:145], v[170:171], v[144:145]
	v_pk_add_f32 v[140:141], v[146:147], v[140:141]
	v_pk_add_f32 v[144:145], v[144:145], v[144:145] op_sel:[0,1] op_sel_hi:[1,0]
	v_pk_add_f32 v[140:141], v[140:141], v[140:141] op_sel:[0,1] op_sel_hi:[1,0]
	v_add_f32_e32 v136, v136, v137
	v_add_f32_e32 v138, v138, v139
	v_mov_b32_e32 v145, v132
	v_mov_b32_e32 v141, v133
	v_mov_b32_e32 v137, v134
	v_mov_b32_e32 v139, v135
	v_pk_add_f32 v[132:133], v[144:145], v[140:141]
	v_pk_add_f32 v[134:135], v[136:137], v[138:139]
	s_lshl_b32 s10, s46, 1
	v_pk_add_f32 v[132:133], v[132:133], v[134:135]
	v_mov_b32_e32 v159, v149
	v_add_f32_e32 v132, v132, v133
	v_fmamk_f32 v132, v132, 0x3a800000, v180
	v_cmp_gt_f32_e32 vcc, s49, v132
	v_mul_f32_e32 v133, 0x4b800000, v132
	s_add_i32 s51, s51, 1
	v_cndmask_b32_e32 v132, v132, v133, vcc
	v_rsq_f32_e32 v132, v132
	s_nop 0
	v_mul_f32_e32 v133, 0x45800000, v132
	v_cndmask_b32_e32 v134, v132, v133, vcc
	v_mov_b32_e32 v132, v129
	v_mov_b32_e32 v133, v130
	v_mov_b32_e32 v129, v131
	v_pk_add_f32 v[128:129], v[132:133], v[128:129]
	v_and_b32_e32 v131, 64, v178
	v_add_f32_e32 v128, v128, v129
	v_mul_f32_e32 v129, v134, v134
	v_mul_f32_e32 v128, v128, v129
	v_fmamk_f32 v128, v128, 0x3b800000, v180
	v_cmp_gt_f32_e32 vcc, s49, v128
	v_mul_f32_e32 v129, 0x4b800000, v128
	v_add_u32_e32 v131, 64, v131
	v_cndmask_b32_e32 v128, v128, v129, vcc
	v_rsq_f32_e32 v128, v128
	s_nop 0
	v_mul_f32_e32 v129, 0x45800000, v128
	v_cndmask_b32_e32 v128, v128, v129, vcc
	v_max3_f32 v129, v112, s50, v113
	v_max3_f32 v129, v129, v114, v115
	v_max3_f32 v129, v129, v116, v117
	v_max3_f32 v129, v129, v118, v119
	v_max3_f32 v129, v129, v120, v121
	v_max3_f32 v129, v129, v122, v123
	v_max3_f32 v129, v129, v124, v125
	v_max3_f32 v129, v129, v126, v127
	v_max3_f32 v129, v129, v96, v97
	v_max3_f32 v129, v129, v98, v99
	v_max3_f32 v129, v129, v100, v101
	v_max3_f32 v129, v129, v102, v103
	v_max3_f32 v129, v129, v104, v105
	v_max3_f32 v129, v129, v106, v107
	v_max3_f32 v129, v129, v108, v109
	v_max3_f32 v129, v129, v110, v111
	v_max3_f32 v129, v129, v80, v81
	v_max3_f32 v129, v129, v82, v83
	v_max3_f32 v129, v129, v84, v85
	v_max3_f32 v129, v129, v86, v87
	v_max3_f32 v129, v129, v88, v89
	v_max3_f32 v129, v129, v90, v91
	v_max3_f32 v129, v129, v92, v93
	v_max3_f32 v129, v129, v94, v95
	v_max3_f32 v129, v129, v64, v65
	v_max3_f32 v129, v129, v66, v67
	v_max3_f32 v129, v129, v68, v69
	v_max3_f32 v129, v129, v70, v71
	v_max3_f32 v129, v129, v72, v73
	v_max3_f32 v129, v129, v74, v75
	v_max3_f32 v129, v129, v76, v77
	v_max3_f32 v129, v129, v78, v79
	v_max3_f32 v129, v129, v48, v49
	v_max3_f32 v129, v129, v50, v51
	v_max3_f32 v129, v129, v52, v53
	v_max3_f32 v129, v129, v54, v55
	v_max3_f32 v129, v129, v56, v57
	v_max3_f32 v129, v129, v58, v59
	v_max3_f32 v129, v129, v60, v61
	v_max3_f32 v129, v129, v62, v63
	v_max3_f32 v129, v129, v32, v33
	v_max3_f32 v129, v129, v34, v35
	v_max3_f32 v129, v129, v36, v37
	v_max3_f32 v129, v129, v38, v39
	v_max3_f32 v129, v129, v40, v41
	v_max3_f32 v129, v129, v42, v43
	v_max3_f32 v129, v129, v44, v45
	v_max3_f32 v129, v129, v46, v47
	v_max3_f32 v129, v129, v16, v17
	v_max3_f32 v129, v129, v18, v19
	v_max3_f32 v129, v129, v20, v21
	v_max3_f32 v129, v129, v22, v23
	v_max3_f32 v129, v129, v24, v25
	v_max3_f32 v129, v129, v26, v27
	v_max3_f32 v129, v129, v28, v29
	v_max3_f32 v129, v129, v30, v31
	v_max3_f32 v129, v129, v0, v1
	v_max3_f32 v129, v129, v2, v3
	v_max3_f32 v129, v129, v4, v5
	v_max3_f32 v129, v129, v6, v7
	v_max3_f32 v129, v129, v8, v9
	v_max3_f32 v129, v129, v10, v11
	v_mul_f32_e32 v128, v134, v128
	v_max3_f32 v129, v129, v12, v13
	v_max3_f32 v130, v129, v14, v15
	v_mul_f32_e32 v129, 0x3db8aa3b, v128
	v_xor_b32_e32 v128, 32, v178
	v_cmp_lt_i32_e32 vcc, v128, v131
	v_mul_f32_e32 v130, v129, v130
	s_nop 0
	v_cndmask_b32_e32 v128, v178, v128, vcc
	v_lshlrev_b32_e32 v128, 2, v128
	ds_bpermute_b32 v131, v128, v130
	s_waitcnt lgkmcnt(0)
	v_max_f32_e32 v131, v131, v131
	v_max_f32_e32 v130, v130, v131
	v_fma_f32 v112, v129, v112, -v130
	v_exp_f32_e32 v112, v112
	v_fma_f32 v113, v129, v113, -v130
	v_exp_f32_e32 v113, v113
	v_fma_f32 v114, v129, v114, -v130
	v_exp_f32_e32 v114, v114
	v_fma_f32 v115, v129, v115, -v130
	v_exp_f32_e32 v115, v115
	v_fma_f32 v116, v129, v116, -v130
	v_add_f32_e32 v131, 0, v112
	v_exp_f32_e32 v132, v116
	v_add_f32_e32 v131, v113, v131
	v_add_f32_e32 v131, v114, v131
	v_add_f32_e32 v131, v115, v131
	v_fma_f32 v117, v129, v117, -v130
	v_add_f32_e32 v116, v132, v131
	v_exp_f32_e32 v131, v117
	v_fma_f32 v117, v129, v118, -v130
	v_exp_f32_e32 v133, v117
	v_fma_f32 v117, v129, v119, -v130
	v_exp_f32_e32 v119, v117
	v_fma_f32 v117, v129, v120, -v130
	v_exp_f32_e32 v120, v117
	v_fma_f32 v117, v129, v121, -v130
	v_add_f32_e32 v116, v131, v116
	v_exp_f32_e32 v121, v117
	v_fma_f32 v117, v129, v122, -v130
	v_add_f32_e32 v116, v133, v116
	v_exp_f32_e32 v122, v117
	v_fma_f32 v117, v129, v123, -v130
	v_add_f32_e32 v116, v119, v116
	v_exp_f32_e32 v123, v117
	v_fma_f32 v117, v129, v124, -v130
	v_add_f32_e32 v116, v120, v116
	v_exp_f32_e32 v124, v117
	v_fma_f32 v117, v129, v125, -v130
	v_add_f32_e32 v116, v121, v116
	v_exp_f32_e32 v125, v117
	v_fma_f32 v117, v129, v126, -v130
	v_add_f32_e32 v116, v122, v116
	v_exp_f32_e32 v126, v117
	v_fma_f32 v117, v129, v127, -v130
	v_add_f32_e32 v116, v123, v116
	v_exp_f32_e32 v127, v117
	v_fma_f32 v96, v129, v96, -v130
	v_add_f32_e32 v116, v124, v116
	v_exp_f32_e32 v96, v96
	v_fma_f32 v97, v129, v97, -v130
	v_add_f32_e32 v116, v125, v116
	v_exp_f32_e32 v97, v97
	v_fma_f32 v98, v129, v98, -v130
	v_add_f32_e32 v116, v126, v116
	v_exp_f32_e32 v98, v98
	v_fma_f32 v99, v129, v99, -v130
	v_add_f32_e32 v134, v127, v116
	v_exp_f32_e32 v99, v99
	v_fma_f32 v100, v129, v100, -v130
	v_cvt_pk_bf16_f32 v116, v112, v113
	v_cvt_pk_bf16_f32 v112, v120, v121
	v_add_f32_e32 v120, v96, v134
	v_exp_f32_e32 v121, v100
	v_add_f32_e32 v120, v97, v120
	v_add_f32_e32 v120, v98, v120
	v_add_f32_e32 v120, v99, v120
	v_fma_f32 v101, v129, v101, -v130
	v_add_f32_e32 v100, v121, v120
	v_exp_f32_e32 v120, v101
	v_fma_f32 v101, v129, v102, -v130
	v_cvt_pk_bf16_f32 v113, v122, v123
	v_exp_f32_e32 v122, v101
	v_fma_f32 v101, v129, v103, -v130
	v_exp_f32_e32 v103, v101
	v_fma_f32 v101, v129, v104, -v130
	v_exp_f32_e32 v104, v101
	v_fma_f32 v101, v129, v105, -v130
	v_add_f32_e32 v100, v120, v100
	v_exp_f32_e32 v105, v101
	v_fma_f32 v101, v129, v106, -v130
	v_add_f32_e32 v100, v122, v100
	v_exp_f32_e32 v106, v101
	v_fma_f32 v101, v129, v107, -v130
	v_add_f32_e32 v100, v103, v100
	v_exp_f32_e32 v107, v101
	v_fma_f32 v101, v129, v108, -v130
	v_add_f32_e32 v100, v104, v100
	v_exp_f32_e32 v108, v101
	v_fma_f32 v101, v129, v109, -v130
	v_add_f32_e32 v100, v105, v100
	v_exp_f32_e32 v109, v101
	v_fma_f32 v101, v129, v110, -v130
	v_add_f32_e32 v100, v106, v100
	v_exp_f32_e32 v110, v101
	v_fma_f32 v101, v129, v111, -v130
	v_add_f32_e32 v100, v107, v100
	v_exp_f32_e32 v111, v101
	v_fma_f32 v80, v129, v80, -v130
	v_add_f32_e32 v100, v108, v100
	v_exp_f32_e32 v80, v80
	v_fma_f32 v81, v129, v81, -v130
	v_add_f32_e32 v100, v109, v100
	v_exp_f32_e32 v81, v81
	v_fma_f32 v82, v129, v82, -v130
	v_add_f32_e32 v100, v110, v100
	v_exp_f32_e32 v82, v82
	v_fma_f32 v83, v129, v83, -v130
	v_add_f32_e32 v123, v111, v100
	v_exp_f32_e32 v83, v83
	v_fma_f32 v84, v129, v84, -v130
	v_cvt_pk_bf16_f32 v100, v96, v97
	v_cvt_pk_bf16_f32 v96, v104, v105
	v_add_f32_e32 v104, v80, v123
	v_exp_f32_e32 v105, v84
	v_add_f32_e32 v104, v81, v104
	v_add_f32_e32 v104, v82, v104
	v_add_f32_e32 v104, v83, v104
	v_fma_f32 v85, v129, v85, -v130
	v_add_f32_e32 v84, v105, v104
	v_exp_f32_e32 v104, v85
	v_fma_f32 v85, v129, v86, -v130
	v_cvt_pk_bf16_f32 v97, v106, v107
	v_exp_f32_e32 v106, v85
	v_fma_f32 v85, v129, v87, -v130
	v_exp_f32_e32 v87, v85
	v_fma_f32 v85, v129, v88, -v130
	v_exp_f32_e32 v88, v85
	v_fma_f32 v85, v129, v89, -v130
	v_add_f32_e32 v84, v104, v84
	v_exp_f32_e32 v89, v85
	v_fma_f32 v85, v129, v90, -v130
	v_add_f32_e32 v84, v106, v84
	v_exp_f32_e32 v90, v85
	v_fma_f32 v85, v129, v91, -v130
	v_add_f32_e32 v84, v87, v84
	v_exp_f32_e32 v91, v85
	v_fma_f32 v85, v129, v92, -v130
	v_add_f32_e32 v84, v88, v84
	v_exp_f32_e32 v92, v85
	v_fma_f32 v85, v129, v93, -v130
	v_add_f32_e32 v84, v89, v84
	v_exp_f32_e32 v93, v85
	v_fma_f32 v85, v129, v94, -v130
	v_add_f32_e32 v84, v90, v84
	v_exp_f32_e32 v94, v85
	v_fma_f32 v85, v129, v95, -v130
	v_add_f32_e32 v84, v91, v84
	v_exp_f32_e32 v95, v85
	v_fma_f32 v64, v129, v64, -v130
	v_add_f32_e32 v84, v92, v84
	v_exp_f32_e32 v64, v64
	v_fma_f32 v65, v129, v65, -v130
	v_add_f32_e32 v84, v93, v84
	v_exp_f32_e32 v65, v65
	v_fma_f32 v66, v129, v66, -v130
	v_add_f32_e32 v84, v94, v84
	v_exp_f32_e32 v66, v66
	v_fma_f32 v67, v129, v67, -v130
	v_add_f32_e32 v107, v95, v84
	v_exp_f32_e32 v67, v67
	v_fma_f32 v68, v129, v68, -v130
	v_cvt_pk_bf16_f32 v84, v80, v81
	v_cvt_pk_bf16_f32 v80, v88, v89
	v_add_f32_e32 v88, v64, v107
	v_exp_f32_e32 v89, v68
	v_add_f32_e32 v88, v65, v88
	v_add_f32_e32 v88, v66, v88
	v_add_f32_e32 v88, v67, v88
	v_fma_f32 v69, v129, v69, -v130
	v_add_f32_e32 v68, v89, v88
	v_exp_f32_e32 v88, v69
	v_fma_f32 v69, v129, v70, -v130
	v_cvt_pk_bf16_f32 v81, v90, v91
	v_exp_f32_e32 v90, v69
	v_fma_f32 v69, v129, v71, -v130
	v_exp_f32_e32 v71, v69
	v_fma_f32 v69, v129, v72, -v130
	v_exp_f32_e32 v72, v69
	v_fma_f32 v69, v129, v73, -v130
	v_add_f32_e32 v68, v88, v68
	v_exp_f32_e32 v73, v69
	v_fma_f32 v69, v129, v74, -v130
	v_add_f32_e32 v68, v90, v68
	v_exp_f32_e32 v74, v69
	v_fma_f32 v69, v129, v75, -v130
	v_add_f32_e32 v68, v71, v68
	v_exp_f32_e32 v75, v69
	v_fma_f32 v69, v129, v76, -v130
	v_add_f32_e32 v68, v72, v68
	v_exp_f32_e32 v76, v69
	v_fma_f32 v69, v129, v77, -v130
	v_add_f32_e32 v68, v73, v68
	v_exp_f32_e32 v77, v69
	v_fma_f32 v69, v129, v78, -v130
	v_add_f32_e32 v68, v74, v68
	v_exp_f32_e32 v78, v69
	v_fma_f32 v69, v129, v79, -v130
	v_add_f32_e32 v68, v75, v68
	v_exp_f32_e32 v79, v69
	v_fma_f32 v48, v129, v48, -v130
	v_add_f32_e32 v68, v76, v68
	v_exp_f32_e32 v48, v48
	v_fma_f32 v49, v129, v49, -v130
	v_add_f32_e32 v68, v77, v68
	v_exp_f32_e32 v49, v49
	v_fma_f32 v50, v129, v50, -v130
	v_add_f32_e32 v68, v78, v68
	v_exp_f32_e32 v50, v50
	v_fma_f32 v51, v129, v51, -v130
	v_add_f32_e32 v91, v79, v68
	v_exp_f32_e32 v51, v51
	v_fma_f32 v52, v129, v52, -v130
	v_cvt_pk_bf16_f32 v68, v64, v65
	v_cvt_pk_bf16_f32 v64, v72, v73
	v_add_f32_e32 v72, v48, v91
	v_exp_f32_e32 v73, v52
	v_add_f32_e32 v72, v49, v72
	v_add_f32_e32 v72, v50, v72
	v_add_f32_e32 v72, v51, v72
	v_fma_f32 v53, v129, v53, -v130
	v_add_f32_e32 v52, v73, v72
	v_exp_f32_e32 v72, v53
	v_fma_f32 v53, v129, v54, -v130
	v_cvt_pk_bf16_f32 v65, v74, v75
	v_exp_f32_e32 v74, v53
	v_fma_f32 v53, v129, v55, -v130
	v_exp_f32_e32 v55, v53
	v_fma_f32 v53, v129, v56, -v130
	v_exp_f32_e32 v56, v53
	v_fma_f32 v53, v129, v57, -v130
	v_add_f32_e32 v52, v72, v52
	v_exp_f32_e32 v57, v53
	v_fma_f32 v53, v129, v58, -v130
	v_add_f32_e32 v52, v74, v52
	v_exp_f32_e32 v58, v53
	v_fma_f32 v53, v129, v59, -v130
	v_add_f32_e32 v52, v55, v52
	v_exp_f32_e32 v59, v53
	v_fma_f32 v53, v129, v60, -v130
	v_add_f32_e32 v52, v56, v52
	v_exp_f32_e32 v60, v53
	v_fma_f32 v53, v129, v61, -v130
	v_add_f32_e32 v52, v57, v52
	v_exp_f32_e32 v61, v53
	v_fma_f32 v53, v129, v62, -v130
	v_add_f32_e32 v52, v58, v52
	v_exp_f32_e32 v62, v53
	v_fma_f32 v53, v129, v63, -v130
	v_add_f32_e32 v52, v59, v52
	v_exp_f32_e32 v63, v53
	v_fma_f32 v32, v129, v32, -v130
	v_add_f32_e32 v52, v60, v52
	v_exp_f32_e32 v32, v32
	v_fma_f32 v33, v129, v33, -v130
	v_add_f32_e32 v52, v61, v52
	v_exp_f32_e32 v33, v33
	v_fma_f32 v34, v129, v34, -v130
	v_add_f32_e32 v52, v62, v52
	v_exp_f32_e32 v34, v34
	v_fma_f32 v35, v129, v35, -v130
	v_add_f32_e32 v75, v63, v52
	v_exp_f32_e32 v35, v35
	v_fma_f32 v36, v129, v36, -v130
	v_cvt_pk_bf16_f32 v52, v48, v49
	v_cvt_pk_bf16_f32 v48, v56, v57
	v_add_f32_e32 v56, v32, v75
	v_exp_f32_e32 v57, v36
	v_add_f32_e32 v56, v33, v56
	v_add_f32_e32 v56, v34, v56
	v_add_f32_e32 v56, v35, v56
	v_fma_f32 v37, v129, v37, -v130
	v_add_f32_e32 v36, v57, v56
	v_exp_f32_e32 v56, v37
	v_fma_f32 v37, v129, v38, -v130
	v_cvt_pk_bf16_f32 v49, v58, v59
	v_exp_f32_e32 v58, v37
	v_fma_f32 v37, v129, v39, -v130
	v_exp_f32_e32 v39, v37
	v_fma_f32 v37, v129, v40, -v130
	v_exp_f32_e32 v40, v37
	v_fma_f32 v37, v129, v41, -v130
	v_add_f32_e32 v36, v56, v36
	v_exp_f32_e32 v41, v37
	v_fma_f32 v37, v129, v42, -v130
	v_add_f32_e32 v36, v58, v36
	v_exp_f32_e32 v42, v37
	v_fma_f32 v37, v129, v43, -v130
	v_add_f32_e32 v36, v39, v36
	v_exp_f32_e32 v43, v37
	v_fma_f32 v37, v129, v44, -v130
	v_add_f32_e32 v36, v40, v36
	v_exp_f32_e32 v44, v37
	v_fma_f32 v37, v129, v45, -v130
	v_add_f32_e32 v36, v41, v36
	v_exp_f32_e32 v45, v37
	v_fma_f32 v37, v129, v46, -v130
	v_add_f32_e32 v36, v42, v36
	v_exp_f32_e32 v46, v37
	v_fma_f32 v37, v129, v47, -v130
	v_add_f32_e32 v36, v43, v36
	v_exp_f32_e32 v47, v37
	v_fma_f32 v16, v129, v16, -v130
	v_add_f32_e32 v36, v44, v36
	v_exp_f32_e32 v16, v16
	v_fma_f32 v17, v129, v17, -v130
	v_add_f32_e32 v36, v45, v36
	v_exp_f32_e32 v17, v17
	v_fma_f32 v18, v129, v18, -v130
	v_add_f32_e32 v36, v46, v36
	v_exp_f32_e32 v18, v18
	v_fma_f32 v19, v129, v19, -v130
	v_add_f32_e32 v59, v47, v36
	v_exp_f32_e32 v19, v19
	v_fma_f32 v20, v129, v20, -v130
	v_cvt_pk_bf16_f32 v36, v32, v33
	v_cvt_pk_bf16_f32 v32, v40, v41
	v_add_f32_e32 v40, v16, v59
	v_exp_f32_e32 v41, v20
	v_add_f32_e32 v40, v17, v40
	v_add_f32_e32 v40, v18, v40
	v_add_f32_e32 v40, v19, v40
	v_fma_f32 v21, v129, v21, -v130
	v_add_f32_e32 v20, v41, v40
	v_exp_f32_e32 v40, v21
	v_fma_f32 v21, v129, v22, -v130
	v_cvt_pk_bf16_f32 v33, v42, v43
	v_exp_f32_e32 v42, v21
	v_fma_f32 v21, v129, v23, -v130
	v_exp_f32_e32 v23, v21
	v_fma_f32 v21, v129, v24, -v130
	v_exp_f32_e32 v24, v21
	v_fma_f32 v21, v129, v25, -v130
	v_add_f32_e32 v20, v40, v20
	v_exp_f32_e32 v25, v21
	v_fma_f32 v21, v129, v26, -v130
	v_add_f32_e32 v20, v42, v20
	v_exp_f32_e32 v26, v21
	v_fma_f32 v21, v129, v27, -v130
	v_add_f32_e32 v20, v23, v20
	v_exp_f32_e32 v27, v21
	v_fma_f32 v21, v129, v28, -v130
	v_add_f32_e32 v20, v24, v20
	v_exp_f32_e32 v28, v21
	v_fma_f32 v21, v129, v29, -v130
	v_add_f32_e32 v20, v25, v20
	v_exp_f32_e32 v29, v21
	v_fma_f32 v21, v129, v30, -v130
	v_add_f32_e32 v20, v26, v20
	v_exp_f32_e32 v30, v21
	v_fma_f32 v21, v129, v31, -v130
	v_add_f32_e32 v20, v27, v20
	v_exp_f32_e32 v31, v21
	v_fma_f32 v0, v129, v0, -v130
	v_add_f32_e32 v20, v28, v20
	v_exp_f32_e32 v0, v0
	v_fma_f32 v1, v129, v1, -v130
	v_add_f32_e32 v20, v29, v20
	v_exp_f32_e32 v1, v1
	v_fma_f32 v2, v129, v2, -v130
	v_add_f32_e32 v20, v30, v20
	v_exp_f32_e32 v2, v2
	v_fma_f32 v3, v129, v3, -v130
	v_add_f32_e32 v43, v31, v20
	v_exp_f32_e32 v3, v3
	v_fma_f32 v4, v129, v4, -v130
	v_cvt_pk_bf16_f32 v20, v16, v17
	v_cvt_pk_bf16_f32 v16, v24, v25
	v_add_f32_e32 v24, v0, v43
	v_exp_f32_e32 v4, v4
	v_fma_f32 v5, v129, v5, -v130
	v_add_f32_e32 v24, v1, v24
	v_exp_f32_e32 v5, v5
	v_fma_f32 v6, v129, v6, -v130
	v_add_f32_e32 v24, v2, v24
	v_exp_f32_e32 v6, v6
	v_fma_f32 v7, v129, v7, -v130
	v_add_f32_e32 v24, v3, v24
	v_exp_f32_e32 v7, v7
	v_fma_f32 v8, v129, v8, -v130
	v_add_f32_e32 v24, v4, v24
	v_exp_f32_e32 v8, v8
	v_fma_f32 v9, v129, v9, -v130
	v_add_f32_e32 v24, v5, v24
	v_exp_f32_e32 v9, v9
	v_fma_f32 v10, v129, v10, -v130
	v_add_f32_e32 v24, v6, v24
	v_exp_f32_e32 v10, v10
	v_fma_f32 v11, v129, v11, -v130
	v_add_f32_e32 v24, v7, v24
	v_exp_f32_e32 v11, v11
	v_fma_f32 v12, v129, v12, -v130
	v_add_f32_e32 v24, v8, v24
	v_exp_f32_e32 v12, v12
	v_fma_f32 v13, v129, v13, -v130
	v_add_f32_e32 v24, v9, v24
	v_exp_f32_e32 v13, v13
	v_fma_f32 v14, v129, v14, -v130
	v_add_f32_e32 v24, v10, v24
	v_exp_f32_e32 v14, v14
	v_fma_f32 v15, v129, v15, -v130
	v_add_f32_e32 v24, v11, v24
	v_exp_f32_e32 v15, v15
	v_add_f32_e32 v24, v12, v24
	v_add_f32_e32 v24, v13, v24
	v_add_f32_e32 v24, v14, v24
	v_cvt_pk_bf16_f32 v22, v41, v40
	v_add_f32_e32 v40, v15, v24
	v_cvt_pk_bf16_f32 v21, v18, v19
	v_cvt_pk_bf16_f32 v18, v28, v29
	v_cvt_pk_bf16_f32 v28, v0, v1
	ds_bpermute_b32 v0, v128, v40
	v_cvt_pk_bf16_f32 v117, v114, v115
	v_cvt_pk_bf16_f32 v118, v132, v131
	v_cvt_pk_bf16_f32 v119, v133, v119
	v_cvt_pk_bf16_f32 v114, v124, v125
	v_cvt_pk_bf16_f32 v115, v126, v127
	v_cvt_pk_bf16_f32 v101, v98, v99
	v_cvt_pk_bf16_f32 v102, v121, v120
	v_cvt_pk_bf16_f32 v103, v122, v103
	v_cvt_pk_bf16_f32 v98, v108, v109
	v_cvt_pk_bf16_f32 v99, v110, v111
	v_cvt_pk_bf16_f32 v85, v82, v83
	v_cvt_pk_bf16_f32 v86, v105, v104
	v_cvt_pk_bf16_f32 v87, v106, v87
	v_cvt_pk_bf16_f32 v82, v92, v93
	v_cvt_pk_bf16_f32 v83, v94, v95
	v_cvt_pk_bf16_f32 v69, v66, v67
	v_cvt_pk_bf16_f32 v70, v89, v88
	v_cvt_pk_bf16_f32 v71, v90, v71
	v_cvt_pk_bf16_f32 v66, v76, v77
	v_cvt_pk_bf16_f32 v67, v78, v79
	v_cvt_pk_bf16_f32 v53, v50, v51
	v_cvt_pk_bf16_f32 v54, v73, v72
	v_cvt_pk_bf16_f32 v55, v74, v55
	v_cvt_pk_bf16_f32 v50, v60, v61
	v_cvt_pk_bf16_f32 v51, v62, v63
	v_cvt_pk_bf16_f32 v37, v34, v35
	v_cvt_pk_bf16_f32 v38, v57, v56
	v_cvt_pk_bf16_f32 v39, v58, v39
	v_cvt_pk_bf16_f32 v34, v44, v45
	v_cvt_pk_bf16_f32 v35, v46, v47
	v_cvt_pk_bf16_f32 v23, v42, v23
	v_cvt_pk_bf16_f32 v17, v26, v27
	v_cvt_pk_bf16_f32 v19, v30, v31
	v_cvt_pk_bf16_f32 v29, v2, v3
	v_cvt_pk_bf16_f32 v30, v4, v5
	v_cvt_pk_bf16_f32 v31, v6, v7
	v_cvt_pk_bf16_f32 v24, v8, v9
	v_cvt_pk_bf16_f32 v25, v10, v11
	v_cvt_pk_bf16_f32 v26, v12, v13
	v_cvt_pk_bf16_f32 v27, v14, v15
	v_lshl_add_u64 v[60:61], v[160:161], 0, s[38:39]
	s_waitcnt lgkmcnt(0)
	v_add_f32_e32 v72, v40, v0
	s_barrier
	s_waitcnt vmcnt(0)
	ds_write_b128 v172, v[228:231]
	ds_write_b128 v172, v[224:227] offset:16
	ds_write_b128 v172, v[216:219] offset:32
	ds_write_b128 v172, v[212:215] offset:48
	ds_write_b128 v172, v[232:235] offset:35840
	ds_write_b128 v172, v[246:249] offset:35856
	ds_write_b128 v172, v[240:243] offset:35872
	ds_write_b128 v172, v[236:239] offset:35888
	v_lshl_add_u64 v[12:13], v[160:161], 0, s[40:41]
	v_lshl_add_u64 v[60:61], v[160:161], 0, s[44:45]
	global_load_dwordx4 v[0:3], v[164:165], off offset:2048
	global_load_dwordx4 v[4:7], v[12:13], off offset:48
	global_load_dwordx4 v[8:11], v[12:13], off offset:32
	s_nop 0
	global_load_dwordx4 v[12:15], v[12:13], off offset:16
	s_nop 0
	global_load_dwordx4 v[40:43], v[166:167], off offset:2048
	global_load_dwordx4 v[44:47], v[60:61], off offset:48
	global_load_dwordx4 v[56:59], v[60:61], off offset:32
	s_nop 0
	global_load_dwordx4 v[60:63], v[60:61], off offset:16
	s_waitcnt vmcnt(7)
	ds_write_b128 v173, v[0:3]
	s_waitcnt vmcnt(4)
	ds_write_b128 v174, v[12:15]
	ds_write_b128 v175, v[8:11]
	ds_write_b128 v179, v[4:7]
	s_waitcnt vmcnt(3)
	ds_write_b128 v182, v[40:43]
	s_waitcnt vmcnt(0)
	ds_write_b128 v183, v[60:63]
	ds_write_b128 v184, v[56:59]
	ds_write_b128 v185, v[44:47]
	v_div_scale_f32 v0, s[4:5], v72, v72, 1.0
	v_rcp_f32_e32 v1, v0
	s_waitcnt lgkmcnt(0)
	s_barrier
	v_fma_f32 v2, -v0, v1, 1.0
	v_fmac_f32_e32 v1, v2, v1
	v_div_scale_f32 v2, vcc, 1.0, v72, 1.0
	v_mul_f32_e32 v3, v2, v1
	v_fma_f32 v4, -v0, v3, v2
	v_fmac_f32_e32 v3, v4, v1
	v_fma_f32 v0, -v0, v3, v2
	v_div_fmas_f32 v0, v0, v1, v3
	v_div_fixup_f32 v44, v0, v72, 1.0
	v_lshl_add_u64 v[0:1], s[12:13], 0, v[162:163]
	v_lshl_add_u64 v[0:1], v[0:1], 0, s[10:11]
	v_lshl_add_u64 v[46:47], v[0:1], 0, v[158:159]
	v_mbcnt_lo_u32_b32 v40, -1, 0
	v_mbcnt_hi_u32_b32 v40, -1, v40
	v_and_b32_e32 v40, 32, v40
	v_lshrrev_b32_e32 v40, 2, v40
	v_mov_b32_e32 v41, 0
	v_lshl_add_u64 v[124:125], v[46:47], 0, v[40:41]
	ds_read_b64_tr_b16 v[56:57], v186
	ds_read_b64_tr_b16 v[58:59], v186 offset:4480
	ds_read_b64_tr_b16 v[60:61], v186 offset:8960
	ds_read_b64_tr_b16 v[62:63], v186 offset:13440
	ds_read_b64_tr_b16 v[88:89], v186 offset:17920
	ds_read_b64_tr_b16 v[90:91], v186 offset:22400
	ds_read_b64_tr_b16 v[92:93], v186 offset:26880
	ds_read_b64_tr_b16 v[94:95], v186 offset:31360
	ds_read_b64_tr_b16 v[104:105], v186 offset:35840
	ds_read_b64_tr_b16 v[106:107], v186 offset:40320
	ds_read_b64_tr_b16 v[108:109], v186 offset:44800
	ds_read_b64_tr_b16 v[110:111], v186 offset:49280
	ds_read_b64_tr_b16 v[120:121], v186 offset:53760
	ds_read_b64_tr_b16 v[122:123], v186 offset:58240
	s_mov_b64 s[4:5], 0
	s_waitcnt lgkmcnt(12)
	v_mfma_f32_32x32x16_bf16 v[0:15], v[56:59], v[116:119], 0
	v_add_u32_e32 v40, v187, v177
	ds_read_b64_tr_b16 v[56:57], v186 offset:62720
	ds_read_b64_tr_b16 v[58:59], v40
	s_waitcnt lgkmcnt(12)
	v_mfma_f32_32x32x16_bf16 v[0:15], v[60:63], v[112:115], v[0:15]
	v_add_u32_e32 v40, v188, v177
	v_add_u32_e32 v42, v189, v177
	ds_read_b64_tr_b16 v[60:61], v40
	ds_read_b64_tr_b16 v[62:63], v42
	s_waitcnt lgkmcnt(12)
	v_mfma_f32_32x32x16_bf16 v[0:15], v[88:91], v[100:103], v[0:15]
	v_add_u32_e32 v40, v190, v177
	v_add_u32_e32 v42, v191, v177
	ds_read_b64_tr_b16 v[88:89], v40
	ds_read_b64_tr_b16 v[90:91], v42
	s_waitcnt lgkmcnt(12)
	v_mfma_f32_32x32x16_bf16 v[0:15], v[92:95], v[96:99], v[0:15]
	v_add_u32_e32 v40, v192, v177
	v_add_u32_e32 v42, v193, v177
	ds_read_b64_tr_b16 v[92:93], v40
	ds_read_b64_tr_b16 v[94:95], v42
	s_waitcnt lgkmcnt(12)
	v_mfma_f32_32x32x16_bf16 v[0:15], v[104:107], v[84:87], v[0:15]
	v_add_u32_e32 v40, v194, v177
	v_add_u32_e32 v42, v195, v177
	ds_read_b64_tr_b16 v[104:105], v40
	ds_read_b64_tr_b16 v[106:107], v42
	s_waitcnt lgkmcnt(12)
	v_mfma_f32_32x32x16_bf16 v[0:15], v[108:111], v[80:83], v[0:15]
	v_add_u32_e32 v40, v196, v177
	v_add_u32_e32 v42, v197, v177
	ds_read_b64_tr_b16 v[108:109], v40
	ds_read_b64_tr_b16 v[110:111], v42
	s_waitcnt lgkmcnt(12)
	v_mfma_f32_32x32x16_bf16 v[0:15], v[120:123], v[68:71], v[0:15]
	v_add_u32_e32 v40, v198, v177
	v_add_u32_e32 v42, v199, v177
	ds_read_b64_tr_b16 v[120:121], v40
	ds_read_b64_tr_b16 v[122:123], v42
	s_waitcnt lgkmcnt(12)
	v_mfma_f32_32x32x16_bf16 v[0:15], v[56:59], v[64:67], v[0:15]
	v_add_u32_e32 v40, v200, v177
	v_add_u32_e32 v42, v201, v177
	ds_read_b64_tr_b16 v[56:57], v40
	ds_read_b64_tr_b16 v[58:59], v42
	s_waitcnt lgkmcnt(12)
	v_mfma_f32_32x32x16_bf16 v[0:15], v[60:63], v[52:55], v[0:15]
	v_add_u32_e32 v40, v202, v177
	v_add_u32_e32 v42, v203, v177
	ds_read_b64_tr_b16 v[60:61], v40
	ds_read_b64_tr_b16 v[62:63], v42
	s_waitcnt lgkmcnt(12)
	v_mfma_f32_32x32x16_bf16 v[0:15], v[88:91], v[48:51], v[0:15]
	ds_read_b64_tr_b16 v[88:89], v186 offset:64
	ds_read_b64_tr_b16 v[90:91], v186 offset:4544
	s_waitcnt lgkmcnt(12)
	v_mfma_f32_32x32x16_bf16 v[0:15], v[92:95], v[36:39], v[0:15]
	ds_read_b64_tr_b16 v[92:93], v186 offset:9024
	ds_read_b64_tr_b16 v[94:95], v186 offset:13504
	s_waitcnt lgkmcnt(12)
	v_mfma_f32_32x32x16_bf16 v[0:15], v[104:107], v[32:35], v[0:15]
	ds_read_b64_tr_b16 v[104:105], v186 offset:17984
	ds_read_b64_tr_b16 v[106:107], v186 offset:22464
	s_waitcnt lgkmcnt(12)
	v_mfma_f32_32x32x16_bf16 v[0:15], v[108:111], v[20:23], v[0:15]
	ds_read_b64_tr_b16 v[108:109], v186 offset:26944
	ds_read_b64_tr_b16 v[110:111], v186 offset:31424
	s_waitcnt lgkmcnt(12)
	v_mfma_f32_32x32x16_bf16 v[0:15], v[120:123], v[16:19], v[0:15]
	ds_read_b64_tr_b16 v[120:121], v186 offset:35904
	ds_read_b64_tr_b16 v[122:123], v186 offset:40384
	s_waitcnt lgkmcnt(12)
	v_mfma_f32_32x32x16_bf16 v[0:15], v[56:59], v[28:31], v[0:15]
	ds_read_b64_tr_b16 v[56:57], v186 offset:44864
	ds_read_b64_tr_b16 v[58:59], v186 offset:49344
	s_waitcnt lgkmcnt(12)
	v_mfma_f32_32x32x16_bf16 v[0:15], v[60:63], v[24:27], v[0:15]
	ds_read_b64_tr_b16 v[60:61], v186 offset:53824
	ds_read_b64_tr_b16 v[62:63], v186 offset:58304
	s_nop 11
	v_pk_mul_f32 v[0:1], v[0:1], v[44:45] op_sel_hi:[1,0]
	v_pk_mul_f32 v[2:3], v[2:3], v[44:45] op_sel_hi:[1,0]
	v_pk_mul_f32 v[4:5], v[4:5], v[44:45] op_sel_hi:[1,0]
	v_pk_mul_f32 v[6:7], v[6:7], v[44:45] op_sel_hi:[1,0]
	v_cvt_pk_bf16_f32 v0, v0, v1
	v_cvt_pk_bf16_f32 v1, v2, v3
	v_cvt_pk_bf16_f32 v2, v4, v5
	v_cvt_pk_bf16_f32 v3, v6, v7
	s_nop 1
	v_permlane32_swap_b32_e32 v0, v2
	v_permlane32_swap_b32_e32 v1, v3
	global_store_dwordx4 v[124:125], v[0:3], off
	v_pk_mul_f32 v[8:9], v[8:9], v[44:45] op_sel_hi:[1,0]
	v_pk_mul_f32 v[10:11], v[10:11], v[44:45] op_sel_hi:[1,0]
	v_pk_mul_f32 v[12:13], v[12:13], v[44:45] op_sel_hi:[1,0]
	v_pk_mul_f32 v[14:15], v[14:15], v[44:45] op_sel_hi:[1,0]
	v_cvt_pk_bf16_f32 v4, v8, v9
	v_cvt_pk_bf16_f32 v5, v10, v11
	v_cvt_pk_bf16_f32 v6, v12, v13
	v_cvt_pk_bf16_f32 v7, v14, v15
	s_nop 1
	v_permlane32_swap_b32_e32 v4, v6
	v_permlane32_swap_b32_e32 v5, v7
	global_store_dwordx4 v[124:125], v[4:7], off offset:32
	s_nop 1
	s_waitcnt lgkmcnt(12)
	v_mfma_f32_32x32x16_bf16 v[0:15], v[88:91], v[116:119], 0
	v_add_u32_e32 v40, v187, v204
	ds_read_b64_tr_b16 v[88:89], v186 offset:62784
	ds_read_b64_tr_b16 v[90:91], v40
	s_waitcnt lgkmcnt(12)
	v_mfma_f32_32x32x16_bf16 v[0:15], v[92:95], v[112:115], v[0:15]
	v_add_u32_e32 v40, v188, v204
	v_add_u32_e32 v42, v189, v204
	ds_read_b64_tr_b16 v[92:93], v40
	ds_read_b64_tr_b16 v[94:95], v42
	s_waitcnt lgkmcnt(12)
	v_mfma_f32_32x32x16_bf16 v[0:15], v[104:107], v[100:103], v[0:15]
	v_add_u32_e32 v40, v190, v204
	v_add_u32_e32 v42, v191, v204
	ds_read_b64_tr_b16 v[104:105], v40
	ds_read_b64_tr_b16 v[106:107], v42
	s_waitcnt lgkmcnt(12)
	v_mfma_f32_32x32x16_bf16 v[0:15], v[108:111], v[96:99], v[0:15]
	v_add_u32_e32 v40, v192, v204
	v_add_u32_e32 v42, v193, v204
	ds_read_b64_tr_b16 v[108:109], v40
	ds_read_b64_tr_b16 v[110:111], v42
	s_waitcnt lgkmcnt(12)
	v_mfma_f32_32x32x16_bf16 v[0:15], v[120:123], v[84:87], v[0:15]
	v_add_u32_e32 v40, v194, v204
	v_add_u32_e32 v42, v195, v204
	ds_read_b64_tr_b16 v[120:121], v40
	ds_read_b64_tr_b16 v[122:123], v42
	s_waitcnt lgkmcnt(12)
	v_mfma_f32_32x32x16_bf16 v[0:15], v[56:59], v[80:83], v[0:15]
	v_add_u32_e32 v40, v196, v204
	v_add_u32_e32 v42, v197, v204
	ds_read_b64_tr_b16 v[56:57], v40
	ds_read_b64_tr_b16 v[58:59], v42
	s_waitcnt lgkmcnt(12)
	v_mfma_f32_32x32x16_bf16 v[0:15], v[60:63], v[68:71], v[0:15]
	v_add_u32_e32 v40, v198, v204
	v_add_u32_e32 v42, v199, v204
	ds_read_b64_tr_b16 v[60:61], v40
	ds_read_b64_tr_b16 v[62:63], v42
	s_waitcnt lgkmcnt(12)
	v_mfma_f32_32x32x16_bf16 v[0:15], v[88:91], v[64:67], v[0:15]
	v_add_u32_e32 v40, v200, v204
	v_add_u32_e32 v42, v201, v204
	ds_read_b64_tr_b16 v[88:89], v40
	ds_read_b64_tr_b16 v[90:91], v42
	s_waitcnt lgkmcnt(12)
	v_mfma_f32_32x32x16_bf16 v[0:15], v[92:95], v[52:55], v[0:15]
	v_add_u32_e32 v40, v202, v204
	v_add_u32_e32 v42, v203, v204
	ds_read_b64_tr_b16 v[92:93], v40
	ds_read_b64_tr_b16 v[94:95], v42
	s_waitcnt lgkmcnt(12)
	v_mfma_f32_32x32x16_bf16 v[0:15], v[104:107], v[48:51], v[0:15]
	ds_read_b64_tr_b16 v[104:105], v186 offset:128
	ds_read_b64_tr_b16 v[106:107], v186 offset:4608
	s_waitcnt lgkmcnt(12)
	v_mfma_f32_32x32x16_bf16 v[0:15], v[108:111], v[36:39], v[0:15]
	ds_read_b64_tr_b16 v[108:109], v186 offset:9088
	ds_read_b64_tr_b16 v[110:111], v186 offset:13568
	s_waitcnt lgkmcnt(12)
	v_mfma_f32_32x32x16_bf16 v[0:15], v[120:123], v[32:35], v[0:15]
	ds_read_b64_tr_b16 v[120:121], v186 offset:18048
	ds_read_b64_tr_b16 v[122:123], v186 offset:22528
	s_waitcnt lgkmcnt(12)
	v_mfma_f32_32x32x16_bf16 v[0:15], v[56:59], v[20:23], v[0:15]
	ds_read_b64_tr_b16 v[56:57], v186 offset:27008
	ds_read_b64_tr_b16 v[58:59], v186 offset:31488
	s_waitcnt lgkmcnt(12)
	v_mfma_f32_32x32x16_bf16 v[0:15], v[60:63], v[16:19], v[0:15]
	ds_read_b64_tr_b16 v[60:61], v186 offset:35968
	ds_read_b64_tr_b16 v[62:63], v186 offset:40448
	s_waitcnt lgkmcnt(12)
	v_mfma_f32_32x32x16_bf16 v[0:15], v[88:91], v[28:31], v[0:15]
	ds_read_b64_tr_b16 v[88:89], v186 offset:44928
	ds_read_b64_tr_b16 v[90:91], v186 offset:49408
	s_waitcnt lgkmcnt(12)
	v_mfma_f32_32x32x16_bf16 v[0:15], v[92:95], v[24:27], v[0:15]
	ds_read_b64_tr_b16 v[92:93], v186 offset:53888
	ds_read_b64_tr_b16 v[94:95], v186 offset:58368
	s_nop 11
	v_pk_mul_f32 v[0:1], v[0:1], v[44:45] op_sel_hi:[1,0]
	v_pk_mul_f32 v[2:3], v[2:3], v[44:45] op_sel_hi:[1,0]
	v_pk_mul_f32 v[4:5], v[4:5], v[44:45] op_sel_hi:[1,0]
	v_pk_mul_f32 v[6:7], v[6:7], v[44:45] op_sel_hi:[1,0]
	v_cvt_pk_bf16_f32 v0, v0, v1
	v_cvt_pk_bf16_f32 v1, v2, v3
	v_cvt_pk_bf16_f32 v2, v4, v5
	v_cvt_pk_bf16_f32 v3, v6, v7
	s_nop 1
	v_permlane32_swap_b32_e32 v0, v2
	v_permlane32_swap_b32_e32 v1, v3
	global_store_dwordx4 v[124:125], v[0:3], off offset:64
	v_pk_mul_f32 v[8:9], v[8:9], v[44:45] op_sel_hi:[1,0]
	v_pk_mul_f32 v[10:11], v[10:11], v[44:45] op_sel_hi:[1,0]
	v_pk_mul_f32 v[12:13], v[12:13], v[44:45] op_sel_hi:[1,0]
	v_pk_mul_f32 v[14:15], v[14:15], v[44:45] op_sel_hi:[1,0]
	v_cvt_pk_bf16_f32 v4, v8, v9
	v_cvt_pk_bf16_f32 v5, v10, v11
	v_cvt_pk_bf16_f32 v6, v12, v13
	v_cvt_pk_bf16_f32 v7, v14, v15
	s_nop 1
	v_permlane32_swap_b32_e32 v4, v6
	v_permlane32_swap_b32_e32 v5, v7
	global_store_dwordx4 v[124:125], v[4:7], off offset:96
	s_nop 1
	s_waitcnt lgkmcnt(12)
	v_mfma_f32_32x32x16_bf16 v[0:15], v[104:107], v[116:119], 0
	v_add_u32_e32 v40, v187, v205
	ds_read_b64_tr_b16 v[104:105], v186 offset:62848
	ds_read_b64_tr_b16 v[106:107], v40
	s_waitcnt lgkmcnt(12)
	v_mfma_f32_32x32x16_bf16 v[0:15], v[108:111], v[112:115], v[0:15]
	v_add_u32_e32 v40, v188, v205
	v_add_u32_e32 v42, v189, v205
	ds_read_b64_tr_b16 v[108:109], v40
	ds_read_b64_tr_b16 v[110:111], v42
	s_waitcnt lgkmcnt(12)
	v_mfma_f32_32x32x16_bf16 v[0:15], v[120:123], v[100:103], v[0:15]
	v_add_u32_e32 v40, v190, v205
	v_add_u32_e32 v42, v191, v205
	ds_read_b64_tr_b16 v[120:121], v40
	ds_read_b64_tr_b16 v[122:123], v42
	s_waitcnt lgkmcnt(12)
	v_mfma_f32_32x32x16_bf16 v[0:15], v[56:59], v[96:99], v[0:15]
	v_add_u32_e32 v40, v192, v205
	v_add_u32_e32 v42, v193, v205
	ds_read_b64_tr_b16 v[56:57], v40
	ds_read_b64_tr_b16 v[58:59], v42
	s_waitcnt lgkmcnt(12)
	v_mfma_f32_32x32x16_bf16 v[0:15], v[60:63], v[84:87], v[0:15]
	v_add_u32_e32 v40, v194, v205
	v_add_u32_e32 v42, v195, v205
	ds_read_b64_tr_b16 v[60:61], v40
	ds_read_b64_tr_b16 v[62:63], v42
	s_waitcnt lgkmcnt(12)
	v_mfma_f32_32x32x16_bf16 v[0:15], v[88:91], v[80:83], v[0:15]
	v_add_u32_e32 v40, v196, v205
	v_add_u32_e32 v42, v197, v205
	ds_read_b64_tr_b16 v[88:89], v40
	ds_read_b64_tr_b16 v[90:91], v42
	s_waitcnt lgkmcnt(12)
	v_mfma_f32_32x32x16_bf16 v[0:15], v[92:95], v[68:71], v[0:15]
	v_add_u32_e32 v40, v198, v205
	v_add_u32_e32 v42, v199, v205
	ds_read_b64_tr_b16 v[92:93], v40
	ds_read_b64_tr_b16 v[94:95], v42
	s_waitcnt lgkmcnt(12)
	v_mfma_f32_32x32x16_bf16 v[0:15], v[104:107], v[64:67], v[0:15]
	v_add_u32_e32 v40, v200, v205
	v_add_u32_e32 v42, v201, v205
	ds_read_b64_tr_b16 v[104:105], v40
	ds_read_b64_tr_b16 v[106:107], v42
	s_waitcnt lgkmcnt(12)
	v_mfma_f32_32x32x16_bf16 v[0:15], v[108:111], v[52:55], v[0:15]
	v_add_u32_e32 v40, v202, v205
	v_add_u32_e32 v42, v203, v205
	ds_read_b64_tr_b16 v[108:109], v40
	ds_read_b64_tr_b16 v[110:111], v42
	s_waitcnt lgkmcnt(12)
	v_mfma_f32_32x32x16_bf16 v[0:15], v[120:123], v[48:51], v[0:15]
	ds_read_b64_tr_b16 v[120:121], v186 offset:192
	ds_read_b64_tr_b16 v[122:123], v186 offset:4672
	s_waitcnt lgkmcnt(12)
	v_mfma_f32_32x32x16_bf16 v[0:15], v[56:59], v[36:39], v[0:15]
	ds_read_b64_tr_b16 v[56:57], v186 offset:9152
	ds_read_b64_tr_b16 v[58:59], v186 offset:13632
	s_waitcnt lgkmcnt(12)
	v_mfma_f32_32x32x16_bf16 v[0:15], v[60:63], v[32:35], v[0:15]
	ds_read_b64_tr_b16 v[60:61], v186 offset:18112
	ds_read_b64_tr_b16 v[62:63], v186 offset:22592
	s_waitcnt lgkmcnt(12)
	v_mfma_f32_32x32x16_bf16 v[0:15], v[88:91], v[20:23], v[0:15]
	ds_read_b64_tr_b16 v[88:89], v186 offset:27072
	ds_read_b64_tr_b16 v[90:91], v186 offset:31552
	s_waitcnt lgkmcnt(12)
	v_mfma_f32_32x32x16_bf16 v[0:15], v[92:95], v[16:19], v[0:15]
	ds_read_b64_tr_b16 v[92:93], v186 offset:36032
	ds_read_b64_tr_b16 v[94:95], v186 offset:40512
	s_waitcnt lgkmcnt(12)
	v_mfma_f32_32x32x16_bf16 v[0:15], v[104:107], v[28:31], v[0:15]
	ds_read_b64_tr_b16 v[104:105], v186 offset:44992
	ds_read_b64_tr_b16 v[106:107], v186 offset:49472
	s_waitcnt lgkmcnt(12)
	v_mfma_f32_32x32x16_bf16 v[0:15], v[108:111], v[24:27], v[0:15]
	ds_read_b64_tr_b16 v[108:109], v186 offset:53952
	ds_read_b64_tr_b16 v[110:111], v186 offset:58432
	s_nop 11
	v_pk_mul_f32 v[0:1], v[0:1], v[44:45] op_sel_hi:[1,0]
	v_pk_mul_f32 v[2:3], v[2:3], v[44:45] op_sel_hi:[1,0]
	v_pk_mul_f32 v[4:5], v[4:5], v[44:45] op_sel_hi:[1,0]
	v_pk_mul_f32 v[6:7], v[6:7], v[44:45] op_sel_hi:[1,0]
	v_cvt_pk_bf16_f32 v0, v0, v1
	v_cvt_pk_bf16_f32 v1, v2, v3
	v_cvt_pk_bf16_f32 v2, v4, v5
	v_cvt_pk_bf16_f32 v3, v6, v7
	s_nop 1
	v_permlane32_swap_b32_e32 v0, v2
	v_permlane32_swap_b32_e32 v1, v3
	global_store_dwordx4 v[124:125], v[0:3], off offset:128
	v_pk_mul_f32 v[8:9], v[8:9], v[44:45] op_sel_hi:[1,0]
	v_pk_mul_f32 v[10:11], v[10:11], v[44:45] op_sel_hi:[1,0]
	v_pk_mul_f32 v[12:13], v[12:13], v[44:45] op_sel_hi:[1,0]
	v_pk_mul_f32 v[14:15], v[14:15], v[44:45] op_sel_hi:[1,0]
	v_cvt_pk_bf16_f32 v4, v8, v9
	v_cvt_pk_bf16_f32 v5, v10, v11
	v_cvt_pk_bf16_f32 v6, v12, v13
	v_cvt_pk_bf16_f32 v7, v14, v15
	s_nop 1
	v_permlane32_swap_b32_e32 v4, v6
	v_permlane32_swap_b32_e32 v5, v7
	global_store_dwordx4 v[124:125], v[4:7], off offset:160
	s_nop 1
	s_waitcnt lgkmcnt(12)
	v_mfma_f32_32x32x16_bf16 v[0:15], v[120:123], v[116:119], 0
	v_add_u32_e32 v40, v187, v206
	ds_read_b64_tr_b16 v[120:121], v186 offset:62912
	ds_read_b64_tr_b16 v[122:123], v40
	s_waitcnt lgkmcnt(12)
	v_mfma_f32_32x32x16_bf16 v[0:15], v[56:59], v[112:115], v[0:15]
	v_add_u32_e32 v40, v188, v206
	v_add_u32_e32 v42, v189, v206
	ds_read_b64_tr_b16 v[56:57], v40
	ds_read_b64_tr_b16 v[58:59], v42
	s_waitcnt lgkmcnt(12)
	v_mfma_f32_32x32x16_bf16 v[0:15], v[60:63], v[100:103], v[0:15]
	v_add_u32_e32 v40, v190, v206
	v_add_u32_e32 v42, v191, v206
	ds_read_b64_tr_b16 v[60:61], v40
	ds_read_b64_tr_b16 v[62:63], v42
	s_waitcnt lgkmcnt(12)
	v_mfma_f32_32x32x16_bf16 v[0:15], v[88:91], v[96:99], v[0:15]
	v_add_u32_e32 v40, v192, v206
	v_add_u32_e32 v42, v193, v206
	ds_read_b64_tr_b16 v[88:89], v40
	ds_read_b64_tr_b16 v[90:91], v42
	s_waitcnt lgkmcnt(12)
	v_mfma_f32_32x32x16_bf16 v[0:15], v[92:95], v[84:87], v[0:15]
	v_add_u32_e32 v40, v194, v206
	v_add_u32_e32 v42, v195, v206
	ds_read_b64_tr_b16 v[92:93], v40
	ds_read_b64_tr_b16 v[94:95], v42
	s_waitcnt lgkmcnt(12)
	v_mfma_f32_32x32x16_bf16 v[0:15], v[104:107], v[80:83], v[0:15]
	v_add_u32_e32 v40, v196, v206
	v_add_u32_e32 v42, v197, v206
	ds_read_b64_tr_b16 v[104:105], v40
	ds_read_b64_tr_b16 v[106:107], v42
	s_waitcnt lgkmcnt(12)
	v_mfma_f32_32x32x16_bf16 v[0:15], v[108:111], v[68:71], v[0:15]
	v_add_u32_e32 v40, v198, v206
	v_add_u32_e32 v42, v199, v206
	ds_read_b64_tr_b16 v[108:109], v40
	ds_read_b64_tr_b16 v[110:111], v42
	s_waitcnt lgkmcnt(12)
	v_mfma_f32_32x32x16_bf16 v[0:15], v[120:123], v[64:67], v[0:15]
	v_add_u32_e32 v40, v200, v206
	v_add_u32_e32 v42, v201, v206
	ds_read_b64_tr_b16 v[120:121], v40
	ds_read_b64_tr_b16 v[122:123], v42
	s_waitcnt lgkmcnt(12)
	v_mfma_f32_32x32x16_bf16 v[0:15], v[56:59], v[52:55], v[0:15]
	v_add_u32_e32 v40, v202, v206
	v_add_u32_e32 v42, v203, v206
	ds_read_b64_tr_b16 v[56:57], v40
	ds_read_b64_tr_b16 v[58:59], v42
	s_waitcnt lgkmcnt(12)
	v_mfma_f32_32x32x16_bf16 v[0:15], v[60:63], v[48:51], v[0:15]
	ds_read_b64_tr_b16 v[60:61], v186 offset:256
	ds_read_b64_tr_b16 v[62:63], v186 offset:4736
	s_waitcnt lgkmcnt(12)
	v_mfma_f32_32x32x16_bf16 v[0:15], v[88:91], v[36:39], v[0:15]
	ds_read_b64_tr_b16 v[88:89], v186 offset:9216
	ds_read_b64_tr_b16 v[90:91], v186 offset:13696
	s_waitcnt lgkmcnt(12)
	v_mfma_f32_32x32x16_bf16 v[0:15], v[92:95], v[32:35], v[0:15]
	ds_read_b64_tr_b16 v[92:93], v186 offset:18176
	ds_read_b64_tr_b16 v[94:95], v186 offset:22656
	s_waitcnt lgkmcnt(12)
	v_mfma_f32_32x32x16_bf16 v[0:15], v[104:107], v[20:23], v[0:15]
	ds_read_b64_tr_b16 v[104:105], v186 offset:27136
	ds_read_b64_tr_b16 v[106:107], v186 offset:31616
	s_waitcnt lgkmcnt(12)
	v_mfma_f32_32x32x16_bf16 v[0:15], v[108:111], v[16:19], v[0:15]
	ds_read_b64_tr_b16 v[108:109], v186 offset:36096
	ds_read_b64_tr_b16 v[110:111], v186 offset:40576
	s_waitcnt lgkmcnt(12)
	v_mfma_f32_32x32x16_bf16 v[0:15], v[120:123], v[28:31], v[0:15]
	ds_read_b64_tr_b16 v[120:121], v186 offset:45056
	ds_read_b64_tr_b16 v[122:123], v186 offset:49536
	s_waitcnt lgkmcnt(12)
	v_mfma_f32_32x32x16_bf16 v[0:15], v[56:59], v[24:27], v[0:15]
	ds_read_b64_tr_b16 v[56:57], v186 offset:54016
	ds_read_b64_tr_b16 v[58:59], v186 offset:58496
	s_nop 11
	v_pk_mul_f32 v[0:1], v[0:1], v[44:45] op_sel_hi:[1,0]
	v_pk_mul_f32 v[2:3], v[2:3], v[44:45] op_sel_hi:[1,0]
	v_pk_mul_f32 v[4:5], v[4:5], v[44:45] op_sel_hi:[1,0]
	v_pk_mul_f32 v[6:7], v[6:7], v[44:45] op_sel_hi:[1,0]
	v_cvt_pk_bf16_f32 v0, v0, v1
	v_cvt_pk_bf16_f32 v1, v2, v3
	v_cvt_pk_bf16_f32 v2, v4, v5
	v_cvt_pk_bf16_f32 v3, v6, v7
	s_nop 1
	v_permlane32_swap_b32_e32 v0, v2
	v_permlane32_swap_b32_e32 v1, v3
	global_store_dwordx4 v[124:125], v[0:3], off offset:192
	v_pk_mul_f32 v[8:9], v[8:9], v[44:45] op_sel_hi:[1,0]
	v_pk_mul_f32 v[10:11], v[10:11], v[44:45] op_sel_hi:[1,0]
	v_pk_mul_f32 v[12:13], v[12:13], v[44:45] op_sel_hi:[1,0]
	v_pk_mul_f32 v[14:15], v[14:15], v[44:45] op_sel_hi:[1,0]
	v_cvt_pk_bf16_f32 v4, v8, v9
	v_cvt_pk_bf16_f32 v5, v10, v11
	v_cvt_pk_bf16_f32 v6, v12, v13
	v_cvt_pk_bf16_f32 v7, v14, v15
	s_nop 1
	v_permlane32_swap_b32_e32 v4, v6
	v_permlane32_swap_b32_e32 v5, v7
	global_store_dwordx4 v[124:125], v[4:7], off offset:224
	s_nop 1
	s_waitcnt lgkmcnt(12)
	v_mfma_f32_32x32x16_bf16 v[0:15], v[60:63], v[116:119], 0
	v_add_u32_e32 v40, v187, v207
	ds_read_b64_tr_b16 v[60:61], v186 offset:62976
	ds_read_b64_tr_b16 v[62:63], v40
	s_waitcnt lgkmcnt(12)
	v_mfma_f32_32x32x16_bf16 v[0:15], v[88:91], v[112:115], v[0:15]
	v_add_u32_e32 v40, v188, v207
	v_add_u32_e32 v42, v189, v207
	ds_read_b64_tr_b16 v[88:89], v40
	ds_read_b64_tr_b16 v[90:91], v42
	s_waitcnt lgkmcnt(12)
	v_mfma_f32_32x32x16_bf16 v[0:15], v[92:95], v[100:103], v[0:15]
	v_add_u32_e32 v40, v190, v207
	v_add_u32_e32 v42, v191, v207
	ds_read_b64_tr_b16 v[92:93], v40
	ds_read_b64_tr_b16 v[94:95], v42
	s_waitcnt lgkmcnt(12)
	v_mfma_f32_32x32x16_bf16 v[0:15], v[104:107], v[96:99], v[0:15]
	v_add_u32_e32 v40, v192, v207
	v_add_u32_e32 v42, v193, v207
	ds_read_b64_tr_b16 v[104:105], v40
	ds_read_b64_tr_b16 v[106:107], v42
	s_waitcnt lgkmcnt(12)
	v_mfma_f32_32x32x16_bf16 v[0:15], v[108:111], v[84:87], v[0:15]
	v_add_u32_e32 v40, v194, v207
	v_add_u32_e32 v42, v195, v207
	ds_read_b64_tr_b16 v[108:109], v40
	ds_read_b64_tr_b16 v[110:111], v42
	s_waitcnt lgkmcnt(12)
	v_mfma_f32_32x32x16_bf16 v[0:15], v[120:123], v[80:83], v[0:15]
	v_add_u32_e32 v40, v196, v207
	v_add_u32_e32 v42, v197, v207
	ds_read_b64_tr_b16 v[120:121], v40
	ds_read_b64_tr_b16 v[122:123], v42
	s_waitcnt lgkmcnt(12)
	v_mfma_f32_32x32x16_bf16 v[0:15], v[56:59], v[68:71], v[0:15]
	v_add_u32_e32 v40, v198, v207
	v_add_u32_e32 v42, v199, v207
	ds_read_b64_tr_b16 v[56:57], v40
	ds_read_b64_tr_b16 v[58:59], v42
	s_waitcnt lgkmcnt(12)
	v_mfma_f32_32x32x16_bf16 v[0:15], v[60:63], v[64:67], v[0:15]
	v_add_u32_e32 v40, v200, v207
	v_add_u32_e32 v42, v201, v207
	ds_read_b64_tr_b16 v[60:61], v40
	ds_read_b64_tr_b16 v[62:63], v42
	s_waitcnt lgkmcnt(12)
	v_mfma_f32_32x32x16_bf16 v[0:15], v[88:91], v[52:55], v[0:15]
	v_add_u32_e32 v40, v202, v207
	v_add_u32_e32 v42, v203, v207
	ds_read_b64_tr_b16 v[88:89], v40
	ds_read_b64_tr_b16 v[90:91], v42
	s_waitcnt lgkmcnt(12)
	v_mfma_f32_32x32x16_bf16 v[0:15], v[92:95], v[48:51], v[0:15]
	ds_read_b64_tr_b16 v[92:93], v186 offset:320
	ds_read_b64_tr_b16 v[94:95], v186 offset:4800
	s_waitcnt lgkmcnt(12)
	v_mfma_f32_32x32x16_bf16 v[0:15], v[104:107], v[36:39], v[0:15]
	ds_read_b64_tr_b16 v[104:105], v186 offset:9280
	ds_read_b64_tr_b16 v[106:107], v186 offset:13760
	s_waitcnt lgkmcnt(12)
	v_mfma_f32_32x32x16_bf16 v[0:15], v[108:111], v[32:35], v[0:15]
	ds_read_b64_tr_b16 v[108:109], v186 offset:18240
	ds_read_b64_tr_b16 v[110:111], v186 offset:22720
	s_waitcnt lgkmcnt(12)
	v_mfma_f32_32x32x16_bf16 v[0:15], v[120:123], v[20:23], v[0:15]
	ds_read_b64_tr_b16 v[120:121], v186 offset:27200
	ds_read_b64_tr_b16 v[122:123], v186 offset:31680
	s_waitcnt lgkmcnt(12)
	v_mfma_f32_32x32x16_bf16 v[0:15], v[56:59], v[16:19], v[0:15]
	ds_read_b64_tr_b16 v[56:57], v186 offset:36160
	ds_read_b64_tr_b16 v[58:59], v186 offset:40640
	s_waitcnt lgkmcnt(12)
	v_mfma_f32_32x32x16_bf16 v[0:15], v[60:63], v[28:31], v[0:15]
	ds_read_b64_tr_b16 v[60:61], v186 offset:45120
	ds_read_b64_tr_b16 v[62:63], v186 offset:49600
	s_waitcnt lgkmcnt(12)
	v_mfma_f32_32x32x16_bf16 v[0:15], v[88:91], v[24:27], v[0:15]
	ds_read_b64_tr_b16 v[88:89], v186 offset:54080
	ds_read_b64_tr_b16 v[90:91], v186 offset:58560
	s_nop 11
	v_pk_mul_f32 v[0:1], v[0:1], v[44:45] op_sel_hi:[1,0]
	v_pk_mul_f32 v[2:3], v[2:3], v[44:45] op_sel_hi:[1,0]
	v_pk_mul_f32 v[4:5], v[4:5], v[44:45] op_sel_hi:[1,0]
	v_pk_mul_f32 v[6:7], v[6:7], v[44:45] op_sel_hi:[1,0]
	v_cvt_pk_bf16_f32 v0, v0, v1
	v_cvt_pk_bf16_f32 v1, v2, v3
	v_cvt_pk_bf16_f32 v2, v4, v5
	v_cvt_pk_bf16_f32 v3, v6, v7
	s_nop 1
	v_permlane32_swap_b32_e32 v0, v2
	v_permlane32_swap_b32_e32 v1, v3
	global_store_dwordx4 v[124:125], v[0:3], off offset:256
	v_pk_mul_f32 v[8:9], v[8:9], v[44:45] op_sel_hi:[1,0]
	v_pk_mul_f32 v[10:11], v[10:11], v[44:45] op_sel_hi:[1,0]
	v_pk_mul_f32 v[12:13], v[12:13], v[44:45] op_sel_hi:[1,0]
	v_pk_mul_f32 v[14:15], v[14:15], v[44:45] op_sel_hi:[1,0]
	v_cvt_pk_bf16_f32 v4, v8, v9
	v_cvt_pk_bf16_f32 v5, v10, v11
	v_cvt_pk_bf16_f32 v6, v12, v13
	v_cvt_pk_bf16_f32 v7, v14, v15
	s_nop 1
	v_permlane32_swap_b32_e32 v4, v6
	v_permlane32_swap_b32_e32 v5, v7
	global_store_dwordx4 v[124:125], v[4:7], off offset:288
	s_nop 1
	s_waitcnt lgkmcnt(12)
	v_mfma_f32_32x32x16_bf16 v[0:15], v[92:95], v[116:119], 0
	v_add_u32_e32 v40, v187, v208
	ds_read_b64_tr_b16 v[92:93], v186 offset:63040
	ds_read_b64_tr_b16 v[94:95], v40
	s_waitcnt lgkmcnt(12)
	v_mfma_f32_32x32x16_bf16 v[0:15], v[104:107], v[112:115], v[0:15]
	v_add_u32_e32 v40, v188, v208
	v_add_u32_e32 v42, v189, v208
	ds_read_b64_tr_b16 v[104:105], v40
	ds_read_b64_tr_b16 v[106:107], v42
	s_waitcnt lgkmcnt(12)
	v_mfma_f32_32x32x16_bf16 v[0:15], v[108:111], v[100:103], v[0:15]
	v_add_u32_e32 v40, v190, v208
	v_add_u32_e32 v42, v191, v208
	ds_read_b64_tr_b16 v[108:109], v40
	ds_read_b64_tr_b16 v[110:111], v42
	s_waitcnt lgkmcnt(12)
	v_mfma_f32_32x32x16_bf16 v[0:15], v[120:123], v[96:99], v[0:15]
	v_add_u32_e32 v40, v192, v208
	v_add_u32_e32 v42, v193, v208
	ds_read_b64_tr_b16 v[120:121], v40
	ds_read_b64_tr_b16 v[122:123], v42
	s_waitcnt lgkmcnt(12)
	v_mfma_f32_32x32x16_bf16 v[0:15], v[56:59], v[84:87], v[0:15]
	v_add_u32_e32 v40, v194, v208
	v_add_u32_e32 v42, v195, v208
	ds_read_b64_tr_b16 v[56:57], v40
	ds_read_b64_tr_b16 v[58:59], v42
	s_waitcnt lgkmcnt(12)
	v_mfma_f32_32x32x16_bf16 v[0:15], v[60:63], v[80:83], v[0:15]
	v_add_u32_e32 v40, v196, v208
	v_add_u32_e32 v42, v197, v208
	ds_read_b64_tr_b16 v[60:61], v40
	ds_read_b64_tr_b16 v[62:63], v42
	s_waitcnt lgkmcnt(12)
	v_mfma_f32_32x32x16_bf16 v[0:15], v[88:91], v[68:71], v[0:15]
	v_add_u32_e32 v40, v198, v208
	v_add_u32_e32 v42, v199, v208
	ds_read_b64_tr_b16 v[88:89], v40
	ds_read_b64_tr_b16 v[90:91], v42
	s_waitcnt lgkmcnt(12)
	v_mfma_f32_32x32x16_bf16 v[0:15], v[92:95], v[64:67], v[0:15]
	v_add_u32_e32 v40, v200, v208
	v_add_u32_e32 v42, v201, v208
	ds_read_b64_tr_b16 v[92:93], v40
	ds_read_b64_tr_b16 v[94:95], v42
	s_waitcnt lgkmcnt(12)
	v_mfma_f32_32x32x16_bf16 v[0:15], v[104:107], v[52:55], v[0:15]
	v_add_u32_e32 v40, v202, v208
	v_add_u32_e32 v42, v203, v208
	ds_read_b64_tr_b16 v[104:105], v40
	ds_read_b64_tr_b16 v[106:107], v42
	s_waitcnt lgkmcnt(12)
	v_mfma_f32_32x32x16_bf16 v[0:15], v[108:111], v[48:51], v[0:15]
	ds_read_b64_tr_b16 v[108:109], v186 offset:384
	ds_read_b64_tr_b16 v[110:111], v186 offset:4864
	s_waitcnt lgkmcnt(12)
	v_mfma_f32_32x32x16_bf16 v[0:15], v[120:123], v[36:39], v[0:15]
	ds_read_b64_tr_b16 v[120:121], v186 offset:9344
	ds_read_b64_tr_b16 v[122:123], v186 offset:13824
	s_waitcnt lgkmcnt(12)
	v_mfma_f32_32x32x16_bf16 v[0:15], v[56:59], v[32:35], v[0:15]
	ds_read_b64_tr_b16 v[56:57], v186 offset:18304
	ds_read_b64_tr_b16 v[58:59], v186 offset:22784
	s_waitcnt lgkmcnt(12)
	v_mfma_f32_32x32x16_bf16 v[0:15], v[60:63], v[20:23], v[0:15]
	ds_read_b64_tr_b16 v[60:61], v186 offset:27264
	ds_read_b64_tr_b16 v[62:63], v186 offset:31744
	s_waitcnt lgkmcnt(12)
	v_mfma_f32_32x32x16_bf16 v[0:15], v[88:91], v[16:19], v[0:15]
	ds_read_b64_tr_b16 v[88:89], v186 offset:36224
	ds_read_b64_tr_b16 v[90:91], v186 offset:40704
	s_waitcnt lgkmcnt(12)
	v_mfma_f32_32x32x16_bf16 v[0:15], v[92:95], v[28:31], v[0:15]
	ds_read_b64_tr_b16 v[92:93], v186 offset:45184
	ds_read_b64_tr_b16 v[94:95], v186 offset:49664
	s_waitcnt lgkmcnt(12)
	v_mfma_f32_32x32x16_bf16 v[0:15], v[104:107], v[24:27], v[0:15]
	ds_read_b64_tr_b16 v[104:105], v186 offset:54144
	ds_read_b64_tr_b16 v[106:107], v186 offset:58624
	s_nop 11
	v_pk_mul_f32 v[0:1], v[0:1], v[44:45] op_sel_hi:[1,0]
	v_pk_mul_f32 v[2:3], v[2:3], v[44:45] op_sel_hi:[1,0]
	v_pk_mul_f32 v[4:5], v[4:5], v[44:45] op_sel_hi:[1,0]
	v_pk_mul_f32 v[6:7], v[6:7], v[44:45] op_sel_hi:[1,0]
	v_cvt_pk_bf16_f32 v0, v0, v1
	v_cvt_pk_bf16_f32 v1, v2, v3
	v_cvt_pk_bf16_f32 v2, v4, v5
	v_cvt_pk_bf16_f32 v3, v6, v7
	s_nop 1
	v_permlane32_swap_b32_e32 v0, v2
	v_permlane32_swap_b32_e32 v1, v3
	global_store_dwordx4 v[124:125], v[0:3], off offset:320
	v_pk_mul_f32 v[8:9], v[8:9], v[44:45] op_sel_hi:[1,0]
	v_pk_mul_f32 v[10:11], v[10:11], v[44:45] op_sel_hi:[1,0]
	v_pk_mul_f32 v[12:13], v[12:13], v[44:45] op_sel_hi:[1,0]
	v_pk_mul_f32 v[14:15], v[14:15], v[44:45] op_sel_hi:[1,0]
	v_cvt_pk_bf16_f32 v4, v8, v9
	v_cvt_pk_bf16_f32 v5, v10, v11
	v_cvt_pk_bf16_f32 v6, v12, v13
	v_cvt_pk_bf16_f32 v7, v14, v15
	s_nop 1
	v_permlane32_swap_b32_e32 v4, v6
	v_permlane32_swap_b32_e32 v5, v7
	global_store_dwordx4 v[124:125], v[4:7], off offset:352
	s_nop 1
	s_waitcnt lgkmcnt(12)
	v_mfma_f32_32x32x16_bf16 v[0:15], v[108:111], v[116:119], 0
	v_add_u32_e32 v40, v187, v209
	ds_read_b64_tr_b16 v[108:109], v186 offset:63104
	ds_read_b64_tr_b16 v[110:111], v40
	s_waitcnt lgkmcnt(12)
	v_mfma_f32_32x32x16_bf16 v[0:15], v[120:123], v[112:115], v[0:15]
	v_add_u32_e32 v40, v188, v209
	v_add_u32_e32 v42, v189, v209
	ds_read_b64_tr_b16 v[120:121], v40
	ds_read_b64_tr_b16 v[122:123], v42
	s_waitcnt lgkmcnt(12)
	v_mfma_f32_32x32x16_bf16 v[0:15], v[56:59], v[100:103], v[0:15]
	v_add_u32_e32 v40, v190, v209
	v_add_u32_e32 v42, v191, v209
	ds_read_b64_tr_b16 v[56:57], v40
	ds_read_b64_tr_b16 v[58:59], v42
	s_waitcnt lgkmcnt(12)
	v_mfma_f32_32x32x16_bf16 v[0:15], v[60:63], v[96:99], v[0:15]
	v_add_u32_e32 v40, v192, v209
	v_add_u32_e32 v42, v193, v209
	ds_read_b64_tr_b16 v[60:61], v40
	ds_read_b64_tr_b16 v[62:63], v42
	s_waitcnt lgkmcnt(12)
	v_mfma_f32_32x32x16_bf16 v[0:15], v[88:91], v[84:87], v[0:15]
	v_add_u32_e32 v40, v194, v209
	v_add_u32_e32 v42, v195, v209
	ds_read_b64_tr_b16 v[88:89], v40
	ds_read_b64_tr_b16 v[90:91], v42
	s_waitcnt lgkmcnt(12)
	v_mfma_f32_32x32x16_bf16 v[0:15], v[92:95], v[80:83], v[0:15]
	v_add_u32_e32 v40, v196, v209
	v_add_u32_e32 v42, v197, v209
	ds_read_b64_tr_b16 v[92:93], v40
	ds_read_b64_tr_b16 v[94:95], v42
	s_waitcnt lgkmcnt(12)
	v_mfma_f32_32x32x16_bf16 v[0:15], v[104:107], v[68:71], v[0:15]
	v_add_u32_e32 v40, v198, v209
	v_add_u32_e32 v42, v199, v209
	ds_read_b64_tr_b16 v[104:105], v40
	ds_read_b64_tr_b16 v[106:107], v42
	s_waitcnt lgkmcnt(12)
	v_mfma_f32_32x32x16_bf16 v[0:15], v[108:111], v[64:67], v[0:15]
	v_add_u32_e32 v40, v200, v209
	v_add_u32_e32 v42, v201, v209
	ds_read_b64_tr_b16 v[108:109], v40
	ds_read_b64_tr_b16 v[110:111], v42
	s_waitcnt lgkmcnt(12)
	v_mfma_f32_32x32x16_bf16 v[0:15], v[120:123], v[52:55], v[0:15]
	v_add_u32_e32 v40, v202, v209
	v_add_u32_e32 v42, v203, v209
	ds_read_b64_tr_b16 v[120:121], v40
	ds_read_b64_tr_b16 v[122:123], v42
	s_waitcnt lgkmcnt(12)
	v_mfma_f32_32x32x16_bf16 v[0:15], v[56:59], v[48:51], v[0:15]
	ds_read_b64_tr_b16 v[56:57], v186 offset:448
	ds_read_b64_tr_b16 v[58:59], v186 offset:4928
	s_waitcnt lgkmcnt(12)
	v_mfma_f32_32x32x16_bf16 v[0:15], v[60:63], v[36:39], v[0:15]
	ds_read_b64_tr_b16 v[60:61], v186 offset:9408
	ds_read_b64_tr_b16 v[62:63], v186 offset:13888
	s_waitcnt lgkmcnt(12)
	v_mfma_f32_32x32x16_bf16 v[0:15], v[88:91], v[32:35], v[0:15]
	ds_read_b64_tr_b16 v[88:89], v186 offset:18368
	ds_read_b64_tr_b16 v[90:91], v186 offset:22848
	s_waitcnt lgkmcnt(12)
	v_mfma_f32_32x32x16_bf16 v[0:15], v[92:95], v[20:23], v[0:15]
	ds_read_b64_tr_b16 v[92:93], v186 offset:27328
	ds_read_b64_tr_b16 v[94:95], v186 offset:31808
	s_waitcnt lgkmcnt(12)
	v_mfma_f32_32x32x16_bf16 v[0:15], v[104:107], v[16:19], v[0:15]
	ds_read_b64_tr_b16 v[104:105], v186 offset:36288
	ds_read_b64_tr_b16 v[106:107], v186 offset:40768
	s_waitcnt lgkmcnt(12)
	v_mfma_f32_32x32x16_bf16 v[0:15], v[108:111], v[28:31], v[0:15]
	ds_read_b64_tr_b16 v[108:109], v186 offset:45248
	ds_read_b64_tr_b16 v[110:111], v186 offset:49728
	s_waitcnt lgkmcnt(12)
	v_mfma_f32_32x32x16_bf16 v[0:15], v[120:123], v[24:27], v[0:15]
	ds_read_b64_tr_b16 v[120:121], v186 offset:54208
	ds_read_b64_tr_b16 v[122:123], v186 offset:58688
	s_nop 11
	v_pk_mul_f32 v[0:1], v[0:1], v[44:45] op_sel_hi:[1,0]
	v_pk_mul_f32 v[2:3], v[2:3], v[44:45] op_sel_hi:[1,0]
	v_pk_mul_f32 v[4:5], v[4:5], v[44:45] op_sel_hi:[1,0]
	v_pk_mul_f32 v[6:7], v[6:7], v[44:45] op_sel_hi:[1,0]
	v_cvt_pk_bf16_f32 v0, v0, v1
	v_cvt_pk_bf16_f32 v1, v2, v3
	v_cvt_pk_bf16_f32 v2, v4, v5
	v_cvt_pk_bf16_f32 v3, v6, v7
	s_nop 1
	v_permlane32_swap_b32_e32 v0, v2
	v_permlane32_swap_b32_e32 v1, v3
	global_store_dwordx4 v[124:125], v[0:3], off offset:384
	v_pk_mul_f32 v[8:9], v[8:9], v[44:45] op_sel_hi:[1,0]
	v_pk_mul_f32 v[10:11], v[10:11], v[44:45] op_sel_hi:[1,0]
	v_pk_mul_f32 v[12:13], v[12:13], v[44:45] op_sel_hi:[1,0]
	v_pk_mul_f32 v[14:15], v[14:15], v[44:45] op_sel_hi:[1,0]
	v_cvt_pk_bf16_f32 v4, v8, v9
	v_cvt_pk_bf16_f32 v5, v10, v11
	v_cvt_pk_bf16_f32 v6, v12, v13
	v_cvt_pk_bf16_f32 v7, v14, v15
	s_nop 1
	v_permlane32_swap_b32_e32 v4, v6
	v_permlane32_swap_b32_e32 v5, v7
	global_store_dwordx4 v[124:125], v[4:7], off offset:416
	s_nop 1
	s_waitcnt lgkmcnt(12)
	v_mfma_f32_32x32x16_bf16 v[0:15], v[56:59], v[116:119], 0
	v_add_u32_e32 v40, v187, v210
	ds_read_b64_tr_b16 v[56:57], v186 offset:63168
	ds_read_b64_tr_b16 v[58:59], v40
	s_waitcnt lgkmcnt(12)
	v_mfma_f32_32x32x16_bf16 v[0:15], v[60:63], v[112:115], v[0:15]
	v_add_u32_e32 v40, v188, v210
	v_add_u32_e32 v42, v189, v210
	ds_read_b64_tr_b16 v[60:61], v40
	ds_read_b64_tr_b16 v[62:63], v42
	s_waitcnt lgkmcnt(12)
	v_mfma_f32_32x32x16_bf16 v[0:15], v[88:91], v[100:103], v[0:15]
	v_add_u32_e32 v40, v190, v210
	v_add_u32_e32 v42, v191, v210
	ds_read_b64_tr_b16 v[88:89], v40
	ds_read_b64_tr_b16 v[90:91], v42
	s_waitcnt lgkmcnt(12)
	v_mfma_f32_32x32x16_bf16 v[0:15], v[92:95], v[96:99], v[0:15]
	v_add_u32_e32 v40, v192, v210
	v_add_u32_e32 v42, v193, v210
	ds_read_b64_tr_b16 v[92:93], v40
	ds_read_b64_tr_b16 v[94:95], v42
	s_waitcnt lgkmcnt(12)
	v_mfma_f32_32x32x16_bf16 v[0:15], v[104:107], v[84:87], v[0:15]
	v_add_u32_e32 v40, v194, v210
	v_add_u32_e32 v42, v195, v210
	ds_read_b64_tr_b16 v[104:105], v40
	ds_read_b64_tr_b16 v[106:107], v42
	s_waitcnt lgkmcnt(12)
	v_mfma_f32_32x32x16_bf16 v[0:15], v[108:111], v[80:83], v[0:15]
	v_add_u32_e32 v40, v196, v210
	v_add_u32_e32 v42, v197, v210
	ds_read_b64_tr_b16 v[108:109], v40
	ds_read_b64_tr_b16 v[110:111], v42
	s_waitcnt lgkmcnt(12)
	v_mfma_f32_32x32x16_bf16 v[0:15], v[120:123], v[68:71], v[0:15]
	v_add_u32_e32 v40, v198, v210
	v_add_u32_e32 v42, v199, v210
	ds_read_b64_tr_b16 v[120:121], v40
	ds_read_b64_tr_b16 v[122:123], v42
	s_waitcnt lgkmcnt(12)
	v_mfma_f32_32x32x16_bf16 v[0:15], v[56:59], v[64:67], v[0:15]
	v_add_u32_e32 v40, v200, v210
	v_add_u32_e32 v42, v201, v210
	ds_read_b64_tr_b16 v[56:57], v40
	ds_read_b64_tr_b16 v[58:59], v42
	s_waitcnt lgkmcnt(12)
	v_mfma_f32_32x32x16_bf16 v[0:15], v[60:63], v[52:55], v[0:15]
	v_add_u32_e32 v40, v202, v210
	v_add_u32_e32 v42, v203, v210
	ds_read_b64_tr_b16 v[60:61], v40
	ds_read_b64_tr_b16 v[62:63], v42
	s_waitcnt lgkmcnt(12)
	v_mfma_f32_32x32x16_bf16 v[0:15], v[88:91], v[48:51], v[0:15]
	s_waitcnt lgkmcnt(10)
	v_mfma_f32_32x32x16_bf16 v[0:15], v[92:95], v[36:39], v[0:15]
	s_waitcnt lgkmcnt(8)
	v_mfma_f32_32x32x16_bf16 v[0:15], v[104:107], v[32:35], v[0:15]
	s_waitcnt lgkmcnt(6)
	v_mfma_f32_32x32x16_bf16 v[0:15], v[108:111], v[20:23], v[0:15]
	s_waitcnt lgkmcnt(4)
	v_mfma_f32_32x32x16_bf16 v[0:15], v[120:123], v[16:19], v[0:15]
	s_waitcnt lgkmcnt(2)
	v_mfma_f32_32x32x16_bf16 v[0:15], v[56:59], v[28:31], v[0:15]
	s_waitcnt lgkmcnt(0)
	v_mfma_f32_32x32x16_bf16 v[0:15], v[60:63], v[24:27], v[0:15]
	s_nop 11
	v_pk_mul_f32 v[0:1], v[0:1], v[44:45] op_sel_hi:[1,0]
	v_pk_mul_f32 v[2:3], v[2:3], v[44:45] op_sel_hi:[1,0]
	v_pk_mul_f32 v[4:5], v[4:5], v[44:45] op_sel_hi:[1,0]
	v_pk_mul_f32 v[6:7], v[6:7], v[44:45] op_sel_hi:[1,0]
	v_cvt_pk_bf16_f32 v0, v0, v1
	v_cvt_pk_bf16_f32 v1, v2, v3
	v_cvt_pk_bf16_f32 v2, v4, v5
	v_cvt_pk_bf16_f32 v3, v6, v7
	s_nop 1
	v_permlane32_swap_b32_e32 v0, v2
	v_permlane32_swap_b32_e32 v1, v3
	global_store_dwordx4 v[124:125], v[0:3], off offset:448
	v_pk_mul_f32 v[8:9], v[8:9], v[44:45] op_sel_hi:[1,0]
	v_pk_mul_f32 v[10:11], v[10:11], v[44:45] op_sel_hi:[1,0]
	v_pk_mul_f32 v[12:13], v[12:13], v[44:45] op_sel_hi:[1,0]
	v_pk_mul_f32 v[14:15], v[14:15], v[44:45] op_sel_hi:[1,0]
	v_cvt_pk_bf16_f32 v4, v8, v9
	v_cvt_pk_bf16_f32 v5, v10, v11
	v_cvt_pk_bf16_f32 v6, v12, v13
	v_cvt_pk_bf16_f32 v7, v14, v15
	s_nop 1
	v_permlane32_swap_b32_e32 v4, v6
	v_permlane32_swap_b32_e32 v5, v7
	global_store_dwordx4 v[124:125], v[4:7], off offset:480
	s_nop 1
	s_barrier
	s_branch .LBB0_751
